# PC1 and PC2 GEMM loops: per-burst priority toggles deleted, static raise for waves 4-7
# baseline (speedup 1.0000x reference)
; #define PG8_STAGE(bufoff, gbase, voff) do { _Pragma("unroll") for (int _i = 0; _i < 2; ++_i) \
;         __builtin_amdgcn_global_load_lds((const unsigned*)((const char*)(gbase) + (voff)[_i]), (LAS unsigned*)(lds + (bufoff) + ldsw + _i * 8192), 16, 0, 0); } while (0)
; #define PG8_WAIT_V(n) asm volatile("s_waitcnt vmcnt(" #n ")" ::: "memory")
; #define PG8_BAR __builtin_amdgcn_s_barrier()
; template <class Epi, class Sched>
; __device__ __forceinline__ void gemm_phase(LAS unsigned char* lds, const Sched& S, const Epi& E, bool natural = false) {
;     const int tid = threadIdx.x, wid = __builtin_amdgcn_readfirstlane(tid >> 6), lane = tid & 63, wr = wid >> 2, wc = wid & 3, fr = lane & 15, fq = lane >> 4;
;     constexpr int nt = K / BK;
;     unsigned voffA[2], voffB0[2], voffB1[2];
; #pragma unroll
;     for (int i = 0; i < 2; ++i) { int R, C; stage_rc(tid * 16 + i * 8192, R, C);
;         const int Rb = 64 * (R >> 5) + (natural ? (R & 31) : perm32(R & 31));
;         voffA[i] = (unsigned)(R * K + C) * 2u; voffB0[i] = (unsigned)(Rb * K + C) * 2u; voffB1[i] = (unsigned)((Rb + 32) * K + C) * 2u; }
;     constexpr size_t kstep = (size_t)(BK * 2);
;     constexpr size_t hstep = (size_t)HALF * K * 2;
;     const unsigned ldsw = (unsigned)wid * 1024u;
;     const int aoff = lds_byte(wr * 64 + fr, fq * 8), boff = lds_byte(wc * 32 + fr, fq * 8);
;     ...
;     Unit cur, nxt; int ui = 0;
;     if (!S.next(0, cur)) return;
;     f32x4 acc[2][2][4][2];
; #pragma unroll
;     for (int a = 0; a < 2; ++a)
; #pragma unroll
;         for (int b = 0; b < 2; ++b)
; #pragma unroll
;             for (int m = 0; m < 4; ++m)
; #pragma unroll
;                 for (int n = 0; n < 2; ++n) acc[a][b][m][n] = (f32x4){0.f, 0.f, 0.f, 0.f};
;     bf16x8 At[4][2], B0[2][2], B1[2][2];
;     const char* cA; const char* cB; S.ptrs(cur, cA, cB);
;     PG8_STAGE(PG8_SB(0, 0), cB, voffB0); PG8_STAGE(PG8_SB(0, 1), cB, voffB1); PG8_STAGE(PG8_SA(0, 0), cA, voffA); PG8_STAGE(PG8_SA(0, 1), cA + hstep, voffA);
;     if (wr == 1) PG8_BAR;
;     PG8_WAIT_V(2); PG8_BAR;
;     PG8_STAGE(PG8_SB(1, 0), cB + kstep, voffB0); PG8_STAGE(PG8_SA(1, 0), cA + kstep, voffA); PG8_STAGE(PG8_SB(1, 1), cB + kstep, voffB1);
;     PG8_WAIT_V(6); PG8_BAR;
.LBB0_481:
	s_cmp_lt_i32 s66, 4
	s_cselect_b64 s[4:5], -1, 0
	s_and_b64 s[4:5], s[4:5], s[0:1]
	s_andn2_b64 vcc, exec, s[4:5]
	s_cbranch_vccnz .LBB0_500
	s_cmpk_gt_i32 s2, 0x2ff
	v_readfirstlane_b32 s1, v190
	s_cbranch_scc1 .LBB0_500
	v_readfirstlane_b32 s100, v190
	s_nop 0
	s_cmp_lt_u32 s100, 0x100
	s_cbranch_scc1 .Lgprio_pc1
	s_setprio 1
.Lgprio_pc1:
	s_waitcnt vmcnt(0)
	v_lshrrev_b32_e32 v3, 5, v190
	v_lshrrev_b32_e32 v6, 1, v190
	v_lshlrev_b32_e32 v0, 4, v190
	v_and_b32_e32 v3, 4, v3
	v_bfe_u32 v5, v190, 2, 2
	v_and_b32_e32 v6, 24, v6
	v_add_u32_e32 v8, 0x2000, v0
	v_or3_b32 v3, v3, v5, v6
	v_and_b32_e32 v5, 32, v190
	s_add_u32 s3, s64, 0x1100000
	v_lshrrev_b32_e32 v2, 6, v8
	s_movk_i32 s0, 0x1c0
	v_bitop3_b32 v9, v0, v5, 48 bitop3:0x6c
	v_and_b32_e32 v10, 64, v190
	s_addc_u32 s33, s65, 0
	v_lshrrev_b32_e32 v1, 7, v8
	v_and_or_b32 v2, v2, s0, v3
	v_or_b32_e32 v0, v9, v10
	v_bfe_u32 v11, v190, 2, 4
	s_movk_i32 s0, 0xf0
	s_add_u32 s34, s64, 0xb00000
	v_lshrrev_b32_e32 v4, 2, v190
	v_lshlrev_b32_e32 v2, 11, v2
	v_or_b32_e32 v5, 0x10000, v0
	v_and_or_b32 v1, v1, s0, v11
	s_movk_i32 s0, 0xc0
	s_addc_u32 s35, s65, 0
	v_or_b32_e32 v164, v2, v5
	v_or_b32_e32 v166, v2, v0
	v_lshl_or_b32 v168, v1, 11, v0
	v_lshrrev_b32_e32 v1, 3, v190
	v_and_or_b32 v2, v4, s0, v3
	s_movk_i32 s0, 0x70
	s_ashr_i32 s37, s2, 31
	v_and_or_b32 v1, v1, s0, v11
	s_lshr_b32 s0, s37, 29
	s_add_i32 s0, s2, s0
	s_lshr_b32 s12, s1, 6
	s_ashr_i32 s6, s0, 3
	s_and_b32 s0, s0, -8
	s_lshr_b32 s16, s1, 8
	s_lshl_b32 s36, s12, 10
	s_sub_i32 s0, s2, s0
	s_cmp_lt_i32 s0, 0
	s_movk_i32 s38, 0x61
	s_cselect_b32 s7, s38, 0x60
	s_mul_i32 s0, s0, s7
	s_add_i32 s0, s0, s6
	s_ashr_i32 s6, s0, 31
	s_lshr_b32 s6, s6, 28
	s_add_i32 s6, s0, s6
	s_ashr_i32 s7, s6, 4
	s_and_b32 s6, s6, 0xfff0
	s_sub_i32 s6, s0, s6
	s_bfe_i32 s0, s6, 0x80000
	s_bfe_u32 s0, s0, 0x2000d
	s_add_i32 s8, s6, s0
	s_bfe_i32 s0, s8, 0x80000
	s_and_b32 s8, s8, 0xfc
	s_sub_i32 s6, s6, s8
	s_lshl_b32 s7, s7, 2
	s_sext_i32_i16 s0, s0
	s_sext_i32_i8 s6, s6
	s_lshr_b32 s0, s0, 2
	s_add_i32 s26, s7, s6
	s_ashr_i32 s27, s26, 31
	s_bfe_i64 s[8:9], s[0:1], 0x100000
	s_lshl_b64 s[6:7], s[26:27], 19
	s_lshl_b64 s[8:9], s[8:9], 19
	s_add_u32 s28, s34, s8
	v_lshlrev_b32_e32 v2, 11, v2
	s_addc_u32 s29, s35, s9
	s_add_i32 s39, s36, 0
	v_or_b32_e32 v172, v2, v0
	s_add_i32 m0, s39, 0x10000
	v_or_b32_e32 v170, v2, v5
	global_load_lds_dwordx4 v172, s[28:29]
	s_add_i32 m0, s39, 0x12000
	v_lshl_or_b32 v174, v1, 11, v0
	global_load_lds_dwordx4 v166, s[28:29]
	s_add_i32 m0, s39, 0x14000
	s_load_dword s43, s[74:75], 0x80
	global_load_lds_dwordx4 v170, s[28:29]
	s_add_i32 m0, s39, 0x16000
	s_add_u32 s24, s3, s6
	s_addc_u32 s25, s33, s7
	s_add_i32 s40, s39, 0x2000
	global_load_lds_dwordx4 v164, s[28:29]
	s_mov_b32 m0, s39
	s_add_u32 s6, s24, 0x40000
	global_load_lds_dwordx4 v174, s[24:25]
	s_mov_b32 m0, s40
	s_addc_u32 s7, s25, 0
	s_add_i32 s41, s39, 0x4000
	global_load_lds_dwordx4 v168, s[24:25]
	s_mov_b32 m0, s41
	s_add_i32 s42, s39, 0x6000
	global_load_lds_dwordx4 v174, s[6:7]
	s_mov_b32 m0, s42
	v_mov_b32_e32 v177, 0
	global_load_lds_dwordx4 v168, s[6:7]
	v_mov_b32_e32 v173, v177
	v_mov_b32_e32 v167, v177
	v_mov_b32_e32 v175, v177
	v_mov_b32_e32 v169, v177
	s_cmp_eq_u32 s16, 1
	s_mov_b32 s44, 0x10000
	s_mov_b32 s45, 0
	v_lshl_add_u64 v[4:5], s[28:29], 0, v[172:173]
	v_lshl_add_u64 v[0:1], s[28:29], 0, v[166:167]
	v_mov_b32_e32 v171, v177
	v_mov_b32_e32 v165, v177
	v_lshl_add_u64 v[2:3], s[24:25], 0, v[174:175]
	s_cselect_b64 s[6:7], -1, 0
	s_cmp_lg_u32 s16, 1
	v_lshl_add_u64 v[6:7], s[24:25], 0, v[168:169]
	s_cbranch_scc1 .LBB0_485
	s_barrier

; #define PG8_STAGE(bufoff, gbase, voff) do { _Pragma("unroll") for (int _i = 0; _i < 2; ++_i) \
;         __builtin_amdgcn_global_load_lds((const unsigned*)((const char*)(gbase) + (voff)[_i]), (LAS unsigned*)(lds + (bufoff) + ldsw + _i * 8192), 16, 0, 0); } while (0)
; #define PG8_LDA(dst, b, h) do { _Pragma("unroll") for (int m = 0; m < 4; ++m) _Pragma("unroll") for (int k = 0; k < 2; ++k) dst[m][k] = *(const LAS bf16x8*)(lds + PG8_SA(b, h) + aoff + m * 2048 + k * 1024); } while (0)
; #define PG8_LDB(dst, b, h) do { _Pragma("unroll") for (int n = 0; n < 2; ++n) _Pragma("unroll") for (int k = 0; k < 2; ++k) dst[n][k] = *(const LAS bf16x8*)(lds + PG8_SB(b, h) + boff + n * 2048 + k * 1024); } while (0)
; #define PG8_MMA(ai, bj, At, Bt) do { __builtin_amdgcn_s_setprio(1); _Pragma("unroll") for (int m = 0; m < 4; ++m) _Pragma("unroll") for (int n = 0; n < 2; ++n) _Pragma("unroll") for (int k = 0; k < 2; ++k) \
;         acc[ai][bj][m][n] = __builtin_amdgcn_mfma_f32_16x16x32_bf16(Bt[n][k], At[m][k], acc[ai][bj][m][n], 0, 0, 0); __builtin_amdgcn_s_setprio(0); } while (0)
; #define PG8_WAIT_V(n) asm volatile("s_waitcnt vmcnt(" #n ")" ::: "memory")
; #define PG8_WAIT_L(n) asm volatile("s_waitcnt lgkmcnt(" #n ")" ::: "memory")
; #define PG8_BAR __builtin_amdgcn_s_barrier()
; #define PG8_SCHED __builtin_amdgcn_sched_barrier(0)
; template <class Epi, class Sched>
; __device__ __forceinline__ void gemm_phase(LAS unsigned char* lds, const Sched& S, const Epi& E, bool natural = false) {
;     ...
;             const char* a1 = cA + (size_t)(t + 1) * kstep;
;             const char* a2 = last ? nA : cA + (size_t)(t + 2) * kstep; const char* b2 = last ? nB : cB + (size_t)(t + 2) * kstep;
;             const char* a3 = a2 + kstep; const char* b3 = b2 + kstep;
;             if constexpr (Epi::MIDHOOK) { if (t == nt / 2) E.mid(acc, cur, wr, wc, fr, fq); }
;             PG8_LDB(B0, 0, 0); PG8_LDB(B1, 0, 1); PG8_SCHED; PG8_LDA(At, 0, 0); PG8_STAGE(PG8_SA(1, 1), a1 + hstep, voffA);
;             PG8_WAIT_V(8); PG8_WAIT_L(0); PG8_BAR; PG8_MMA(0, 0, At, B0); PG8_MMA(0, 1, At, B1); PG8_BAR; PG8_SCHED;
;             PG8_LDA(At, 0, 1); PG8_STAGE(PG8_SB(0, 0), b2, voffB0); PG8_STAGE(PG8_SB(0, 1), b2, voffB1); PG8_STAGE(PG8_SA(0, 0), a2, voffA);
.LBB0_491:
	s_add_u32 s28, s24, s26
	s_addc_u32 s29, s25, s27
	s_add_u32 s28, s28, 0x100
	s_addc_u32 s29, s29, 0
	s_add_u32 s60, s57, s26
	s_addc_u32 s61, s58, s27
	s_cmpk_eq_i32 s26, 0x700
	s_cselect_b32 s60, s56, s60
	s_cselect_b32 s31, s17, s29
	s_cselect_b32 s30, s19, s28
	s_cselect_b32 s61, s55, s61
	s_add_u32 s28, s60, 0x80
	s_addc_u32 s29, s61, 0
	s_add_i32 s68, 0, 0x10000
	v_add_u32_e32 v140, s68, v186
	v_add_u32_e32 v156, s54, v186
	ds_read_b128 v[128:131], v140
	ds_read_b128 v[132:135], v140 offset:1024
	ds_read_b128 v[136:139], v140 offset:2048
	ds_read_b128 v[140:143], v140 offset:3072
	ds_read_b128 v[144:147], v156
	ds_read_b128 v[148:151], v156 offset:1024
	ds_read_b128 v[152:155], v156 offset:2048
	ds_read_b128 v[156:159], v156 offset:3072
	v_lshl_add_u64 v[224:225], v[160:161], 0, s[26:27]
	s_add_i32 m0, s39, 0xc000
	ds_read_b128 v[192:195], v188
	ds_read_b128 v[196:199], v188 offset:1024
	ds_read_b128 v[200:203], v188 offset:2048
	ds_read_b128 v[204:207], v188 offset:3072
	ds_read_b128 v[208:211], v188 offset:4096
	ds_read_b128 v[212:215], v188 offset:5120
	ds_read_b128 v[216:219], v188 offset:6144
	ds_read_b128 v[220:223], v188 offset:7168
	global_load_lds_dwordx4 v[224:225], off
	v_lshl_add_u64 v[224:225], v[162:163], 0, s[26:27]
	s_add_i32 m0, s39, 0xe000
	s_nop 0
	global_load_lds_dwordx4 v[224:225], off
	s_waitcnt vmcnt(8)
	s_waitcnt lgkmcnt(0)
	s_barrier
	s_waitcnt lgkmcnt(0)
	v_mfma_f32_16x16x32_bf16 v[124:127], v[128:131], v[192:195], v[124:127]
	v_mfma_f32_16x16x32_bf16 v[120:123], v[136:139], v[192:195], v[120:123]
	v_mfma_f32_16x16x32_bf16 v[108:111], v[128:131], v[200:203], v[108:111]
	v_mfma_f32_16x16x32_bf16 v[104:107], v[136:139], v[200:203], v[104:107]
	v_mfma_f32_16x16x32_bf16 v[92:95], v[128:131], v[208:211], v[92:95]
	v_mfma_f32_16x16x32_bf16 v[88:91], v[136:139], v[208:211], v[88:91]
	v_mfma_f32_16x16x32_bf16 v[76:79], v[128:131], v[216:219], v[76:79]
	v_mfma_f32_16x16x32_bf16 v[72:75], v[136:139], v[216:219], v[72:75]
	v_mfma_f32_16x16x32_bf16 v[124:127], v[132:135], v[196:199], v[124:127]
	v_mfma_f32_16x16x32_bf16 v[120:123], v[140:143], v[196:199], v[120:123]
	v_mfma_f32_16x16x32_bf16 v[108:111], v[132:135], v[204:207], v[108:111]
	v_mfma_f32_16x16x32_bf16 v[104:107], v[140:143], v[204:207], v[104:107]
	v_mfma_f32_16x16x32_bf16 v[92:95], v[132:135], v[212:215], v[92:95]
	v_mfma_f32_16x16x32_bf16 v[88:91], v[140:143], v[212:215], v[88:91]
	v_mfma_f32_16x16x32_bf16 v[76:79], v[132:135], v[220:223], v[76:79]
	v_mfma_f32_16x16x32_bf16 v[72:75], v[140:143], v[220:223], v[72:75]
	v_mfma_f32_16x16x32_bf16 v[116:119], v[144:147], v[192:195], v[116:119]
	v_mfma_f32_16x16x32_bf16 v[112:115], v[152:155], v[192:195], v[112:115]
	v_mfma_f32_16x16x32_bf16 v[100:103], v[144:147], v[200:203], v[100:103]
	v_mfma_f32_16x16x32_bf16 v[96:99], v[152:155], v[200:203], v[96:99]
	v_mfma_f32_16x16x32_bf16 v[84:87], v[144:147], v[208:211], v[84:87]
	v_mfma_f32_16x16x32_bf16 v[80:83], v[152:155], v[208:211], v[80:83]
	v_mfma_f32_16x16x32_bf16 v[68:71], v[144:147], v[216:219], v[68:71]
	v_mfma_f32_16x16x32_bf16 v[64:67], v[152:155], v[216:219], v[64:67]
	v_mfma_f32_16x16x32_bf16 v[116:119], v[148:151], v[196:199], v[116:119]
	v_mfma_f32_16x16x32_bf16 v[112:115], v[156:159], v[196:199], v[112:115]
	v_mfma_f32_16x16x32_bf16 v[100:103], v[148:151], v[204:207], v[100:103]
	v_mfma_f32_16x16x32_bf16 v[96:99], v[156:159], v[204:207], v[96:99]
	v_mfma_f32_16x16x32_bf16 v[84:87], v[148:151], v[212:215], v[84:87]
	v_mfma_f32_16x16x32_bf16 v[80:83], v[156:159], v[212:215], v[80:83]
	v_mfma_f32_16x16x32_bf16 v[68:71], v[148:151], v[220:223], v[68:71]
	v_mfma_f32_16x16x32_bf16 v[64:67], v[156:159], v[220:223], v[64:67]
	s_barrier
	s_add_i32 s68, s68, s36
	v_lshl_add_u64 v[224:225], s[60:61], 0, v[172:173]
	s_mov_b32 m0, s68
	ds_read_b128 v[192:195], v188 offset:16384
	ds_read_b128 v[196:199], v188 offset:17408
	ds_read_b128 v[200:203], v188 offset:18432
	ds_read_b128 v[204:207], v188 offset:19456
	ds_read_b128 v[208:211], v188 offset:20480
	ds_read_b128 v[212:215], v188 offset:21504
	ds_read_b128 v[216:219], v188 offset:22528
	ds_read_b128 v[220:223], v188 offset:23552
	global_load_lds_dwordx4 v[224:225], off
	v_lshl_add_u64 v[226:227], s[60:61], 0, v[166:167]
	s_add_i32 m0, s68, 0x2000
	s_add_i32 s68, s54, s36
	global_load_lds_dwordx4 v[226:227], off
	v_lshl_add_u64 v[228:229], s[60:61], 0, v[170:171]
	s_mov_b32 m0, s68
	v_lshl_add_u64 v[230:231], s[30:31], 0, v[168:169]
	global_load_lds_dwordx4 v[228:229], off
	v_lshl_add_u64 v[228:229], s[60:61], 0, v[164:165]
	s_add_i32 m0, s68, 0x2000
	s_nop 0
	global_load_lds_dwordx4 v[228:229], off
	v_lshl_add_u64 v[228:229], s[30:31], 0, v[174:175]
	s_mov_b32 m0, s39
	s_nop 0
	global_load_lds_dwordx4 v[228:229], off
	s_mov_b32 m0, s40
	s_nop 0
	global_load_lds_dwordx4 v[230:231], off
	s_waitcnt vmcnt(8)
	s_waitcnt lgkmcnt(0)
	s_barrier
; #define PG8_STAGE(bufoff, gbase, voff) do { _Pragma("unroll") for (int _i = 0; _i < 2; ++_i) \
;         __builtin_amdgcn_global_load_lds((const unsigned*)((const char*)(gbase) + (voff)[_i]), (LAS unsigned*)(lds + (bufoff) + ldsw + _i * 8192), 16, 0, 0); } while (0)
; #define PG8_LDA(dst, b, h) do { _Pragma("unroll") for (int m = 0; m < 4; ++m) _Pragma("unroll") for (int k = 0; k < 2; ++k) dst[m][k] = *(const LAS bf16x8*)(lds + PG8_SA(b, h) + aoff + m * 2048 + k * 1024); } while (0)
; #define PG8_LDB(dst, b, h) do { _Pragma("unroll") for (int n = 0; n < 2; ++n) _Pragma("unroll") for (int k = 0; k < 2; ++k) dst[n][k] = *(const LAS bf16x8*)(lds + PG8_SB(b, h) + boff + n * 2048 + k * 1024); } while (0)
; #define PG8_MMA(ai, bj, At, Bt) do { __builtin_amdgcn_s_setprio(1); _Pragma("unroll") for (int m = 0; m < 4; ++m) _Pragma("unroll") for (int n = 0; n < 2; ++n) _Pragma("unroll") for (int k = 0; k < 2; ++k) \
;         acc[ai][bj][m][n] = __builtin_amdgcn_mfma_f32_16x16x32_bf16(Bt[n][k], At[m][k], acc[ai][bj][m][n], 0, 0, 0); __builtin_amdgcn_s_setprio(0); } while (0)
; #define PG8_WAIT_V(n) asm volatile("s_waitcnt vmcnt(" #n ")" ::: "memory")
; #define PG8_WAIT_L(n) asm volatile("s_waitcnt lgkmcnt(" #n ")" ::: "memory")
; #define PG8_BAR __builtin_amdgcn_s_barrier()
; #define PG8_SCHED __builtin_amdgcn_sched_barrier(0)
; template <class Epi, class Sched>
; __device__ __forceinline__ void gemm_phase(LAS unsigned char* lds, const Sched& S, const Epi& E, bool natural = false) {
;     ...
;             PG8_WAIT_V(8); PG8_WAIT_L(0); PG8_BAR; PG8_MMA(1, 0, At, B0); PG8_MMA(1, 1, At, B1); PG8_BAR; PG8_SCHED;
;             PG8_LDB(B0, 1, 0); PG8_LDB(B1, 1, 1); PG8_SCHED; PG8_LDA(At, 1, 0); PG8_STAGE(PG8_SA(0, 1), a2 + hstep, voffA);
;             PG8_WAIT_V(8); PG8_WAIT_L(0); PG8_BAR; PG8_MMA(0, 0, At, B0); PG8_MMA(0, 1, At, B1); PG8_BAR; PG8_SCHED;
	s_waitcnt lgkmcnt(0)
	v_mfma_f32_16x16x32_bf16 v[60:63], v[128:131], v[192:195], v[60:63]
	v_mfma_f32_16x16x32_bf16 v[56:59], v[136:139], v[192:195], v[56:59]
	v_mfma_f32_16x16x32_bf16 v[44:47], v[128:131], v[200:203], v[44:47]
	v_mfma_f32_16x16x32_bf16 v[40:43], v[136:139], v[200:203], v[40:43]
	v_mfma_f32_16x16x32_bf16 v[28:31], v[128:131], v[208:211], v[28:31]
	v_mfma_f32_16x16x32_bf16 v[24:27], v[136:139], v[208:211], v[24:27]
	v_mfma_f32_16x16x32_bf16 v[12:15], v[128:131], v[216:219], v[12:15]
	v_mfma_f32_16x16x32_bf16 v[8:11], v[136:139], v[216:219], v[8:11]
	v_mfma_f32_16x16x32_bf16 v[60:63], v[132:135], v[196:199], v[60:63]
	v_mfma_f32_16x16x32_bf16 v[56:59], v[140:143], v[196:199], v[56:59]
	v_mfma_f32_16x16x32_bf16 v[44:47], v[132:135], v[204:207], v[44:47]
	v_mfma_f32_16x16x32_bf16 v[40:43], v[140:143], v[204:207], v[40:43]
	v_mfma_f32_16x16x32_bf16 v[28:31], v[132:135], v[212:215], v[28:31]
	v_mfma_f32_16x16x32_bf16 v[24:27], v[140:143], v[212:215], v[24:27]
	v_mfma_f32_16x16x32_bf16 v[12:15], v[132:135], v[220:223], v[12:15]
	v_mfma_f32_16x16x32_bf16 v[8:11], v[140:143], v[220:223], v[8:11]
	v_mfma_f32_16x16x32_bf16 v[52:55], v[144:147], v[192:195], v[52:55]
	v_mfma_f32_16x16x32_bf16 v[48:51], v[152:155], v[192:195], v[48:51]
	v_mfma_f32_16x16x32_bf16 v[36:39], v[144:147], v[200:203], v[36:39]
	v_mfma_f32_16x16x32_bf16 v[32:35], v[152:155], v[200:203], v[32:35]
	v_mfma_f32_16x16x32_bf16 v[20:23], v[144:147], v[208:211], v[20:23]
	v_mfma_f32_16x16x32_bf16 v[16:19], v[152:155], v[208:211], v[16:19]
	v_mfma_f32_16x16x32_bf16 v[4:7], v[144:147], v[216:219], v[4:7]
	v_mfma_f32_16x16x32_bf16 v[0:3], v[152:155], v[216:219], v[0:3]
	v_mfma_f32_16x16x32_bf16 v[52:55], v[148:151], v[196:199], v[52:55]
	v_mfma_f32_16x16x32_bf16 v[48:51], v[156:159], v[196:199], v[48:51]
	v_mfma_f32_16x16x32_bf16 v[36:39], v[148:151], v[204:207], v[36:39]
	v_mfma_f32_16x16x32_bf16 v[32:35], v[156:159], v[204:207], v[32:35]
	v_mfma_f32_16x16x32_bf16 v[20:23], v[148:151], v[212:215], v[20:23]
	v_mfma_f32_16x16x32_bf16 v[16:19], v[156:159], v[212:215], v[16:19]
	v_mfma_f32_16x16x32_bf16 v[4:7], v[148:151], v[220:223], v[4:7]
	v_mfma_f32_16x16x32_bf16 v[0:3], v[156:159], v[220:223], v[0:3]
	s_barrier
	s_add_i32 s60, 0, 0x18000
	s_add_i32 s61, 0, 0x1c000
	v_add_u32_e32 v140, s60, v186
	v_add_u32_e32 v156, s61, v186
	ds_read_b128 v[128:131], v140
	ds_read_b128 v[132:135], v140 offset:1024
	ds_read_b128 v[136:139], v140 offset:2048
	ds_read_b128 v[140:143], v140 offset:3072
	ds_read_b128 v[144:147], v156
	ds_read_b128 v[148:151], v156 offset:1024
	ds_read_b128 v[152:155], v156 offset:2048
	ds_read_b128 v[156:159], v156 offset:3072
	s_add_u32 s30, s30, 0x40000
	s_addc_u32 s31, s31, 0
	s_mov_b32 m0, s41
	v_lshl_add_u64 v[232:233], s[30:31], 0, v[174:175]
	ds_read_b128 v[192:195], v188 offset:32768
	ds_read_b128 v[196:199], v188 offset:33792
	ds_read_b128 v[200:203], v188 offset:34816
	ds_read_b128 v[204:207], v188 offset:35840
	ds_read_b128 v[208:211], v188 offset:36864
	ds_read_b128 v[212:215], v188 offset:37888
	ds_read_b128 v[216:219], v188 offset:38912
	ds_read_b128 v[220:223], v188 offset:39936
	global_load_lds_dwordx4 v[232:233], off
	v_lshl_add_u64 v[232:233], s[30:31], 0, v[168:169]
	s_mov_b32 m0, s42
	s_nop 0
	global_load_lds_dwordx4 v[232:233], off
	s_waitcnt vmcnt(8)
	s_waitcnt lgkmcnt(0)
	s_barrier
	s_waitcnt lgkmcnt(0)
	v_mfma_f32_16x16x32_bf16 v[124:127], v[128:131], v[192:195], v[124:127]
	v_mfma_f32_16x16x32_bf16 v[120:123], v[136:139], v[192:195], v[120:123]
	v_mfma_f32_16x16x32_bf16 v[108:111], v[128:131], v[200:203], v[108:111]
	v_mfma_f32_16x16x32_bf16 v[104:107], v[136:139], v[200:203], v[104:107]
	v_mfma_f32_16x16x32_bf16 v[92:95], v[128:131], v[208:211], v[92:95]
	v_mfma_f32_16x16x32_bf16 v[88:91], v[136:139], v[208:211], v[88:91]
	v_mfma_f32_16x16x32_bf16 v[76:79], v[128:131], v[216:219], v[76:79]
	v_mfma_f32_16x16x32_bf16 v[72:75], v[136:139], v[216:219], v[72:75]
	v_mfma_f32_16x16x32_bf16 v[124:127], v[132:135], v[196:199], v[124:127]
	v_mfma_f32_16x16x32_bf16 v[120:123], v[140:143], v[196:199], v[120:123]
	v_mfma_f32_16x16x32_bf16 v[108:111], v[132:135], v[204:207], v[108:111]
	v_mfma_f32_16x16x32_bf16 v[104:107], v[140:143], v[204:207], v[104:107]
	v_mfma_f32_16x16x32_bf16 v[92:95], v[132:135], v[212:215], v[92:95]
	v_mfma_f32_16x16x32_bf16 v[88:91], v[140:143], v[212:215], v[88:91]
	v_mfma_f32_16x16x32_bf16 v[76:79], v[132:135], v[220:223], v[76:79]
	v_mfma_f32_16x16x32_bf16 v[72:75], v[140:143], v[220:223], v[72:75]
	v_mfma_f32_16x16x32_bf16 v[116:119], v[144:147], v[192:195], v[116:119]
	v_mfma_f32_16x16x32_bf16 v[112:115], v[152:155], v[192:195], v[112:115]
	v_mfma_f32_16x16x32_bf16 v[100:103], v[144:147], v[200:203], v[100:103]
	v_mfma_f32_16x16x32_bf16 v[96:99], v[152:155], v[200:203], v[96:99]
	v_mfma_f32_16x16x32_bf16 v[84:87], v[144:147], v[208:211], v[84:87]
	v_mfma_f32_16x16x32_bf16 v[80:83], v[152:155], v[208:211], v[80:83]
	v_mfma_f32_16x16x32_bf16 v[68:71], v[144:147], v[216:219], v[68:71]
	v_mfma_f32_16x16x32_bf16 v[64:67], v[152:155], v[216:219], v[64:67]
	v_mfma_f32_16x16x32_bf16 v[116:119], v[148:151], v[196:199], v[116:119]
	v_mfma_f32_16x16x32_bf16 v[112:115], v[156:159], v[196:199], v[112:115]
	v_mfma_f32_16x16x32_bf16 v[100:103], v[148:151], v[204:207], v[100:103]
	v_mfma_f32_16x16x32_bf16 v[96:99], v[156:159], v[204:207], v[96:99]
	v_mfma_f32_16x16x32_bf16 v[84:87], v[148:151], v[212:215], v[84:87]
	v_mfma_f32_16x16x32_bf16 v[80:83], v[156:159], v[212:215], v[80:83]
	v_mfma_f32_16x16x32_bf16 v[68:71], v[148:151], v[220:223], v[68:71]
	v_mfma_f32_16x16x32_bf16 v[64:67], v[156:159], v[220:223], v[64:67]
	s_barrier
; #define PG8_STAGE(bufoff, gbase, voff) do { _Pragma("unroll") for (int _i = 0; _i < 2; ++_i) \
;         __builtin_amdgcn_global_load_lds((const unsigned*)((const char*)(gbase) + (voff)[_i]), (LAS unsigned*)(lds + (bufoff) + ldsw + _i * 8192), 16, 0, 0); } while (0)
; #define PG8_LDA(dst, b, h) do { _Pragma("unroll") for (int m = 0; m < 4; ++m) _Pragma("unroll") for (int k = 0; k < 2; ++k) dst[m][k] = *(const LAS bf16x8*)(lds + PG8_SA(b, h) + aoff + m * 2048 + k * 1024); } while (0)
; #define PG8_MMA(ai, bj, At, Bt) do { __builtin_amdgcn_s_setprio(1); _Pragma("unroll") for (int m = 0; m < 4; ++m) _Pragma("unroll") for (int n = 0; n < 2; ++n) _Pragma("unroll") for (int k = 0; k < 2; ++k) \
;         acc[ai][bj][m][n] = __builtin_amdgcn_mfma_f32_16x16x32_bf16(Bt[n][k], At[m][k], acc[ai][bj][m][n], 0, 0, 0); __builtin_amdgcn_s_setprio(0); } while (0)
; #define PG8_WAIT_V(n) asm volatile("s_waitcnt vmcnt(" #n ")" ::: "memory")
; #define PG8_WAIT_L(n) asm volatile("s_waitcnt lgkmcnt(" #n ")" ::: "memory")
; #define PG8_BAR __builtin_amdgcn_s_barrier()
; #define PG8_SCHED __builtin_amdgcn_sched_barrier(0)
; template <class Epi, class Sched>
; __device__ __forceinline__ void gemm_phase(LAS unsigned char* lds, const Sched& S, const Epi& E, bool natural = false) {
;     ...
;             PG8_LDA(At, 1, 1); PG8_STAGE(PG8_SB(1, 0), b3, voffB0); PG8_STAGE(PG8_SB(1, 1), b3, voffB1); PG8_STAGE(PG8_SA(1, 0), a3, voffA);
;             PG8_WAIT_V(8); PG8_WAIT_L(0); PG8_BAR; PG8_MMA(1, 0, At, B0); PG8_MMA(1, 1, At, B1); PG8_BAR; PG8_SCHED;
;         }
	s_add_i32 s30, s60, s36
	v_lshl_add_u64 v[224:225], v[224:225], 0, s[12:13]
	s_mov_b32 m0, s30
	ds_read_b128 v[192:195], v188 offset:49152
	ds_read_b128 v[196:199], v188 offset:50176
	ds_read_b128 v[200:203], v188 offset:51200
	ds_read_b128 v[204:207], v188 offset:52224
	ds_read_b128 v[208:211], v188 offset:53248
	ds_read_b128 v[212:215], v188 offset:54272
	ds_read_b128 v[216:219], v188 offset:55296
	ds_read_b128 v[220:223], v188 offset:56320
	global_load_lds_dwordx4 v[224:225], off
	v_lshl_add_u64 v[224:225], v[226:227], 0, s[12:13]
	s_add_i32 m0, s30, 0x2000
	s_add_i32 s30, s61, s36
	global_load_lds_dwordx4 v[224:225], off
	v_lshl_add_u64 v[224:225], s[28:29], 0, v[170:171]
	s_mov_b32 m0, s30
	s_nop 0
	global_load_lds_dwordx4 v[224:225], off
	v_lshl_add_u64 v[224:225], s[28:29], 0, v[164:165]
	s_add_i32 m0, s30, 0x2000
	s_nop 0
	global_load_lds_dwordx4 v[224:225], off
	v_lshl_add_u64 v[224:225], v[228:229], 0, s[12:13]
	s_mov_b32 m0, s46
	s_nop 0
	global_load_lds_dwordx4 v[224:225], off
	v_lshl_add_u64 v[224:225], v[230:231], 0, s[12:13]
	s_mov_b32 m0, s47
	s_nop 0
	global_load_lds_dwordx4 v[224:225], off
	s_waitcnt vmcnt(8)
	s_waitcnt lgkmcnt(0)
	s_barrier
	s_waitcnt lgkmcnt(0)
	v_mfma_f32_16x16x32_bf16 v[60:63], v[128:131], v[192:195], v[60:63]
	v_mfma_f32_16x16x32_bf16 v[56:59], v[136:139], v[192:195], v[56:59]
	v_mfma_f32_16x16x32_bf16 v[44:47], v[128:131], v[200:203], v[44:47]
	v_mfma_f32_16x16x32_bf16 v[40:43], v[136:139], v[200:203], v[40:43]
	v_mfma_f32_16x16x32_bf16 v[28:31], v[128:131], v[208:211], v[28:31]
	v_mfma_f32_16x16x32_bf16 v[24:27], v[136:139], v[208:211], v[24:27]
	v_mfma_f32_16x16x32_bf16 v[12:15], v[128:131], v[216:219], v[12:15]
	v_mfma_f32_16x16x32_bf16 v[8:11], v[136:139], v[216:219], v[8:11]
	v_mfma_f32_16x16x32_bf16 v[60:63], v[132:135], v[196:199], v[60:63]
	v_mfma_f32_16x16x32_bf16 v[56:59], v[140:143], v[196:199], v[56:59]
	v_mfma_f32_16x16x32_bf16 v[44:47], v[132:135], v[204:207], v[44:47]
	v_mfma_f32_16x16x32_bf16 v[40:43], v[140:143], v[204:207], v[40:43]
	v_mfma_f32_16x16x32_bf16 v[28:31], v[132:135], v[212:215], v[28:31]
	v_mfma_f32_16x16x32_bf16 v[24:27], v[140:143], v[212:215], v[24:27]
	v_mfma_f32_16x16x32_bf16 v[12:15], v[132:135], v[220:223], v[12:15]
	v_mfma_f32_16x16x32_bf16 v[8:11], v[140:143], v[220:223], v[8:11]
	v_mfma_f32_16x16x32_bf16 v[52:55], v[144:147], v[192:195], v[52:55]
	v_mfma_f32_16x16x32_bf16 v[48:51], v[152:155], v[192:195], v[48:51]
	v_mfma_f32_16x16x32_bf16 v[36:39], v[144:147], v[200:203], v[36:39]
	v_mfma_f32_16x16x32_bf16 v[32:35], v[152:155], v[200:203], v[32:35]
	v_mfma_f32_16x16x32_bf16 v[20:23], v[144:147], v[208:211], v[20:23]
	v_mfma_f32_16x16x32_bf16 v[16:19], v[152:155], v[208:211], v[16:19]
	v_mfma_f32_16x16x32_bf16 v[4:7], v[144:147], v[216:219], v[4:7]
	v_mfma_f32_16x16x32_bf16 v[0:3], v[152:155], v[216:219], v[0:3]
	v_mfma_f32_16x16x32_bf16 v[52:55], v[148:151], v[196:199], v[52:55]
	v_mfma_f32_16x16x32_bf16 v[48:51], v[156:159], v[196:199], v[48:51]
	v_mfma_f32_16x16x32_bf16 v[36:39], v[148:151], v[204:207], v[36:39]
	v_mfma_f32_16x16x32_bf16 v[32:35], v[156:159], v[204:207], v[32:35]
	v_mfma_f32_16x16x32_bf16 v[20:23], v[148:151], v[212:215], v[20:23]
	v_mfma_f32_16x16x32_bf16 v[16:19], v[156:159], v[212:215], v[16:19]
	v_mfma_f32_16x16x32_bf16 v[4:7], v[148:151], v[220:223], v[4:7]
	v_mfma_f32_16x16x32_bf16 v[0:3], v[156:159], v[220:223], v[0:3]
	s_barrier
	s_add_i32 s59, s59, 2
	s_add_u32 s26, s26, 0x100
	s_addc_u32 s27, s27, 0
	s_cmp_gt_u32 s59, 13
	s_cbranch_scc1 .LBB0_494

; #define PG8_STAGE(bufoff, gbase, voff) do { _Pragma("unroll") for (int _i = 0; _i < 2; ++_i) \
;         __builtin_amdgcn_global_load_lds((const unsigned*)((const char*)(gbase) + (voff)[_i]), (LAS unsigned*)(lds + (bufoff) + ldsw + _i * 8192), 16, 0, 0); } while (0)
; #define PG8_WAIT_V(n) asm volatile("s_waitcnt vmcnt(" #n ")" ::: "memory")
; #define PG8_BAR __builtin_amdgcn_s_barrier()
; template <class Epi, class Sched>
; __device__ __forceinline__ void gemm_phase(LAS unsigned char* lds, const Sched& S, const Epi& E, bool natural = false) {
;     const int tid = threadIdx.x, wid = __builtin_amdgcn_readfirstlane(tid >> 6), lane = tid & 63, wr = wid >> 2, wc = wid & 3, fr = lane & 15, fq = lane >> 4;
;     constexpr int nt = K / BK;
;     unsigned voffA[2], voffB0[2], voffB1[2];
; #pragma unroll
;     for (int i = 0; i < 2; ++i) { int R, C; stage_rc(tid * 16 + i * 8192, R, C);
;         const int Rb = 64 * (R >> 5) + (natural ? (R & 31) : perm32(R & 31));
;         voffA[i] = (unsigned)(R * K + C) * 2u; voffB0[i] = (unsigned)(Rb * K + C) * 2u; voffB1[i] = (unsigned)((Rb + 32) * K + C) * 2u; }
;     constexpr size_t kstep = (size_t)(BK * 2);
;     constexpr size_t hstep = (size_t)HALF * K * 2;
;     const unsigned ldsw = (unsigned)wid * 1024u;
;     const int aoff = lds_byte(wr * 64 + fr, fq * 8), boff = lds_byte(wc * 32 + fr, fq * 8);
;     ...
;     Unit cur, nxt; int ui = 0;
;     if (!S.next(0, cur)) return;
;     f32x4 acc[2][2][4][2];
; #pragma unroll
;     for (int a = 0; a < 2; ++a)
; #pragma unroll
;         for (int b = 0; b < 2; ++b)
; #pragma unroll
;             for (int m = 0; m < 4; ++m)
; #pragma unroll
;                 for (int n = 0; n < 2; ++n) acc[a][b][m][n] = (f32x4){0.f, 0.f, 0.f, 0.f};
;     bf16x8 At[4][2], B0[2][2], B1[2][2];
;     const char* cA; const char* cB; S.ptrs(cur, cA, cB);
;     PG8_STAGE(PG8_SB(0, 0), cB, voffB0); PG8_STAGE(PG8_SB(0, 1), cB, voffB1); PG8_STAGE(PG8_SA(0, 0), cA, voffA); PG8_STAGE(PG8_SA(0, 1), cA + hstep, voffA);
;     if (wr == 1) PG8_BAR;
;     PG8_WAIT_V(2); PG8_BAR;
;     PG8_STAGE(PG8_SB(1, 0), cB + kstep, voffB0); PG8_STAGE(PG8_SA(1, 0), cA + kstep, voffA); PG8_STAGE(PG8_SB(1, 1), cB + kstep, voffB1);
;     PG8_WAIT_V(6); PG8_BAR;
.LBB0_554:
	s_cmp_lt_i32 s66, 5
	s_cselect_b64 s[4:5], -1, 0
	s_and_b64 s[0:1], s[4:5], s[0:1]
	s_andn2_b64 vcc, exec, s[0:1]
	s_cbranch_vccnz .LBB0_575
	s_cmpk_gt_i32 s2, 0x2ff
	v_readfirstlane_b32 s1, v190
	s_cbranch_scc1 .LBB0_575
	v_readfirstlane_b32 s100, v190
	s_nop 0
	s_cmp_lt_u32 s100, 0x100
	s_cbranch_scc1 .Lgprio_pc2
	s_setprio 1
.Lgprio_pc2:
	s_waitcnt vmcnt(0)
	v_lshlrev_b32_e32 v0, 4, v190
	s_add_u32 s3, s64, 0x7100000
	v_add_u32_e32 v8, 0x2000, v0
	v_and_b32_e32 v4, 32, v190
	s_addc_u32 s28, s65, 0
	v_lshrrev_b32_e32 v1, 7, v8
	v_bfe_u32 v9, v190, 2, 4
	s_movk_i32 s0, 0xf0
	v_lshrrev_b32_e32 v3, 6, v8
	v_bitop3_b32 v10, v0, v4, 48 bitop3:0x6c
	v_and_b32_e32 v11, 64, v190
	s_add_u32 s29, s64, 0xd00000
	v_and_or_b32 v1, v1, s0, v9
	v_and_b32_e32 v3, 0x1c0, v3
	v_or_b32_e32 v0, v10, v11
	s_addc_u32 s30, s65, 0
	v_and_or_b32 v3, v1, 31, v3
	v_lshl_or_b32 v132, v1, 11, v0
	v_lshrrev_b32_e32 v1, 3, v190
	s_movk_i32 s0, 0x70
	s_ashr_i32 s33, s2, 31
	v_and_or_b32 v1, v1, s0, v9
	s_lshr_b32 s0, s33, 29
	s_add_i32 s0, s2, s0
	s_lshr_b32 s8, s1, 6
	s_ashr_i32 s4, s0, 3
	s_and_b32 s0, s0, -8
	s_lshr_b32 s12, s1, 8
	s_lshl_b32 s31, s8, 10
	s_sub_i32 s0, s2, s0
	s_cmp_lt_i32 s0, 0
	s_movk_i32 s34, 0x61
	s_cselect_b32 s5, s34, 0x60
	s_mul_i32 s0, s0, s5
	s_add_i32 s0, s0, s4
	s_ashr_i32 s4, s0, 31
	s_lshr_b32 s4, s4, 28
	s_add_i32 s4, s0, s4
	s_ashr_i32 s5, s4, 4
	s_and_b32 s4, s4, 0xfff0
	s_sub_i32 s4, s0, s4
	s_bfe_i32 s0, s4, 0x80000
	s_bfe_u32 s0, s0, 0x2000d
	s_add_i32 s6, s4, s0
	s_bfe_i32 s0, s6, 0x80000
	s_and_b32 s6, s6, 0xfc
	s_sub_i32 s4, s4, s6
	s_lshl_b32 s5, s5, 2
	s_sext_i32_i16 s0, s0
	s_sext_i32_i8 s4, s4
	s_lshr_b32 s0, s0, 2
	s_add_i32 s4, s5, s4
	v_lshrrev_b32_e32 v2, 2, v190
	s_ashr_i32 s5, s4, 31
	s_bfe_i64 s[10:11], s[0:1], 0x100000
	v_and_b32_e32 v2, 0xc0, v2
	s_lshl_b64 s[6:7], s[4:5], 19
	s_lshl_b64 s[10:11], s[10:11], 19
	v_and_or_b32 v2, v1, 31, v2
	s_add_u32 s22, s29, s10
	v_lshlrev_b32_e32 v2, 11, v2
	s_addc_u32 s23, s30, s11
	s_add_i32 s35, s31, 0
	v_lshlrev_b32_e32 v3, 11, v3
	v_or_b32_e32 v136, v2, v0
	s_add_i32 m0, s35, 0x10000
	v_or_b32_e32 v4, 0x10000, v0
	v_or_b32_e32 v130, v3, v0
	global_load_lds_dwordx4 v136, s[22:23]
	s_add_i32 m0, s35, 0x12000
	s_waitcnt lgkmcnt(0)
	v_or_b32_e32 v134, v2, v4
	global_load_lds_dwordx4 v130, s[22:23]
	s_add_i32 m0, s35, 0x14000
	v_or_b32_e32 v128, v3, v4
	global_load_lds_dwordx4 v134, s[22:23]
	s_add_i32 m0, s35, 0x16000
	s_add_u32 s20, s3, s6
	s_addc_u32 s21, s28, s7
	s_add_i32 s36, s35, 0x2000
	v_lshl_or_b32 v138, v1, 11, v0
	global_load_lds_dwordx4 v128, s[22:23]
	s_mov_b32 m0, s35
	s_add_u32 s6, s20, 0x40000
	global_load_lds_dwordx4 v138, s[20:21]
	s_mov_b32 m0, s36
	s_addc_u32 s7, s21, 0
	s_add_i32 s37, s35, 0x4000
	global_load_lds_dwordx4 v132, s[20:21]
	s_mov_b32 m0, s37
	s_add_i32 s38, s35, 0x6000
	global_load_lds_dwordx4 v138, s[6:7]
	s_mov_b32 m0, s38
	s_load_dword s39, s[74:75], 0x80
	global_load_lds_dwordx4 v132, s[6:7]
	v_mov_b32_e32 v141, 0
	v_mov_b32_e32 v137, v141
	v_mov_b32_e32 v131, v141
	v_mov_b32_e32 v139, v141
	v_mov_b32_e32 v133, v141
	s_cmp_eq_u32 s12, 1
	s_mov_b32 s40, 0x10000
	s_mov_b32 s5, 0
	v_lshl_add_u64 v[4:5], s[22:23], 0, v[136:137]
	v_lshl_add_u64 v[0:1], s[22:23], 0, v[130:131]
	v_mov_b32_e32 v135, v141
	v_mov_b32_e32 v129, v141
	v_lshl_add_u64 v[2:3], s[20:21], 0, v[138:139]
	s_cselect_b64 s[6:7], -1, 0
	s_cmp_lg_u32 s12, 1
	v_lshl_add_u64 v[6:7], s[20:21], 0, v[132:133]
	s_cbranch_scc1 .LBB0_558
	s_barrier

; #define PG8_STAGE(bufoff, gbase, voff) do { _Pragma("unroll") for (int _i = 0; _i < 2; ++_i) \
;         __builtin_amdgcn_global_load_lds((const unsigned*)((const char*)(gbase) + (voff)[_i]), (LAS unsigned*)(lds + (bufoff) + ldsw + _i * 8192), 16, 0, 0); } while (0)
; #define PG8_LDA(dst, b, h) do { _Pragma("unroll") for (int m = 0; m < 4; ++m) _Pragma("unroll") for (int k = 0; k < 2; ++k) dst[m][k] = *(const LAS bf16x8*)(lds + PG8_SA(b, h) + aoff + m * 2048 + k * 1024); } while (0)
; #define PG8_LDB(dst, b, h) do { _Pragma("unroll") for (int n = 0; n < 2; ++n) _Pragma("unroll") for (int k = 0; k < 2; ++k) dst[n][k] = *(const LAS bf16x8*)(lds + PG8_SB(b, h) + boff + n * 2048 + k * 1024); } while (0)
; #define PG8_MMA(ai, bj, At, Bt) do { __builtin_amdgcn_s_setprio(1); _Pragma("unroll") for (int m = 0; m < 4; ++m) _Pragma("unroll") for (int n = 0; n < 2; ++n) _Pragma("unroll") for (int k = 0; k < 2; ++k) \
;         acc[ai][bj][m][n] = __builtin_amdgcn_mfma_f32_16x16x32_bf16(Bt[n][k], At[m][k], acc[ai][bj][m][n], 0, 0, 0); __builtin_amdgcn_s_setprio(0); } while (0)
; #define PG8_WAIT_V(n) asm volatile("s_waitcnt vmcnt(" #n ")" ::: "memory")
; #define PG8_WAIT_L(n) asm volatile("s_waitcnt lgkmcnt(" #n ")" ::: "memory")
; template <class Epi, class Sched>
; __device__ __forceinline__ void gemm_phase(LAS unsigned char* lds, const Sched& S, const Epi& E, bool natural = false) {
;     ...
;         const bool has_next = S.next(ui + 1, nxt);
;         const char* nA = cA; const char* nB = cB; if (has_next) S.ptrs(nxt, nA, nB);
;         for (int t = 0; t < nt; t += 2) {
;             const bool last = (t == nt - 2);
;             const char* a1 = cA + (size_t)(t + 1) * kstep;
;             const char* a2 = last ? nA : cA + (size_t)(t + 2) * kstep; const char* b2 = last ? nB : cB + (size_t)(t + 2) * kstep;
;             const char* a3 = a2 + kstep; const char* b3 = b2 + kstep;
;             if constexpr (Epi::MIDHOOK) { if (t == nt / 2) E.mid(acc, cur, wr, wc, fr, fq); }
;             PG8_LDB(B0, 0, 0); PG8_LDB(B1, 0, 1); PG8_SCHED; PG8_LDA(At, 0, 0); PG8_STAGE(PG8_SA(1, 1), a1 + hstep, voffA);
;             PG8_WAIT_V(8); PG8_WAIT_L(0); PG8_BAR; PG8_MMA(0, 0, At, B0); PG8_MMA(0, 1, At, B1); PG8_BAR; PG8_SCHED;
;             PG8_LDA(At, 0, 1); PG8_STAGE(PG8_SB(0, 0), b2, voffB0); PG8_STAGE(PG8_SB(0, 1), b2, voffB1); PG8_STAGE(PG8_SA(0, 0), a2, voffA);
.LBB0_563:
	s_ashr_i32 s15, s14, 31
	s_ashr_i32 s13, s12, 31
	s_lshl_b64 s[16:17], s[14:15], 19
	s_lshl_b64 s[18:19], s[12:13], 19
	s_add_u32 s16, s3, s16
	s_addc_u32 s17, s28, s17
	s_add_u32 s18, s29, s18
	s_addc_u32 s19, s30, s19
	s_and_b64 s[24:25], s[0:1], exec
	s_cselect_b32 s13, s17, s21
	s_cselect_b32 s15, s16, s20
	s_cselect_b32 s26, s19, s23
	s_cselect_b32 s27, s18, s22
	s_add_u32 s20, s20, 0x40080
	s_addc_u32 s21, s21, 0
	s_add_u32 s54, s22, 0x100
	s_addc_u32 s55, s23, 0
	s_mov_b32 s56, -2
	ds_read_b128 v[150:153], v156
	ds_read_b128 v[160:163], v156 offset:1024
	ds_read_b128 v[164:167], v156 offset:2048
	ds_read_b128 v[168:171], v156 offset:3072
	ds_read_b128 v[172:175], v157
	ds_read_b128 v[176:179], v157 offset:1024
	ds_read_b128 v[180:183], v157 offset:2048
	ds_read_b128 v[184:187], v157 offset:3072
	s_add_u32 s22, s20, 0xfffc0080
	s_addc_u32 s23, s21, -1
	s_cmp_eq_u32 s56, 12
	s_cselect_b32 s25, s13, s23
	s_cselect_b32 s24, s15, s22
	s_cselect_b32 s23, s26, s55
	s_cselect_b32 s22, s27, s54
	v_lshl_add_u64 v[220:221], s[20:21], 0, v[142:143]
	s_add_i32 m0, s35, 0xc000
	ds_read_b128 v[188:191], v158
	ds_read_b128 v[192:195], v158 offset:1024
	ds_read_b128 v[196:199], v158 offset:2048
	ds_read_b128 v[200:203], v158 offset:3072
	ds_read_b128 v[204:207], v158 offset:4096
	ds_read_b128 v[208:211], v158 offset:5120
	ds_read_b128 v[212:215], v158 offset:6144
	ds_read_b128 v[216:219], v158 offset:7168
	global_load_lds_dwordx4 v[220:221], off
	v_lshl_add_u64 v[220:221], s[20:21], 0, v[144:145]
	s_add_i32 m0, s35, 0xe000
	s_nop 0
	global_load_lds_dwordx4 v[220:221], off
	s_waitcnt vmcnt(8)
	s_waitcnt lgkmcnt(0)
	s_barrier
	s_waitcnt lgkmcnt(0)
	v_mfma_f32_16x16x32_bf16 v[124:127], v[150:153], v[188:191], 0
	v_mfma_f32_16x16x32_bf16 v[120:123], v[164:167], v[188:191], 0
	v_mfma_f32_16x16x32_bf16 v[116:119], v[150:153], v[196:199], 0
	v_mfma_f32_16x16x32_bf16 v[112:115], v[164:167], v[196:199], 0
	v_mfma_f32_16x16x32_bf16 v[104:107], v[150:153], v[204:207], 0
	v_mfma_f32_16x16x32_bf16 v[96:99], v[164:167], v[204:207], 0
	v_mfma_f32_16x16x32_bf16 v[88:91], v[150:153], v[212:215], 0
	v_mfma_f32_16x16x32_bf16 v[80:83], v[164:167], v[212:215], 0
	v_mfma_f32_16x16x32_bf16 v[124:127], v[160:163], v[192:195], v[124:127]
	v_mfma_f32_16x16x32_bf16 v[120:123], v[168:171], v[192:195], v[120:123]
	v_mfma_f32_16x16x32_bf16 v[116:119], v[160:163], v[200:203], v[116:119]
	v_mfma_f32_16x16x32_bf16 v[112:115], v[168:171], v[200:203], v[112:115]
	v_mfma_f32_16x16x32_bf16 v[104:107], v[160:163], v[208:211], v[104:107]
	v_mfma_f32_16x16x32_bf16 v[96:99], v[168:171], v[208:211], v[96:99]
	v_mfma_f32_16x16x32_bf16 v[88:91], v[160:163], v[216:219], v[88:91]
	v_mfma_f32_16x16x32_bf16 v[80:83], v[168:171], v[216:219], v[80:83]
	v_mfma_f32_16x16x32_bf16 v[108:111], v[172:175], v[188:191], 0
	v_mfma_f32_16x16x32_bf16 v[100:103], v[180:183], v[188:191], 0
	v_mfma_f32_16x16x32_bf16 v[92:95], v[172:175], v[196:199], 0
	v_mfma_f32_16x16x32_bf16 v[84:87], v[180:183], v[196:199], 0
	v_mfma_f32_16x16x32_bf16 v[76:79], v[172:175], v[204:207], 0
	v_mfma_f32_16x16x32_bf16 v[72:75], v[180:183], v[204:207], 0
	v_mfma_f32_16x16x32_bf16 v[68:71], v[172:175], v[212:215], 0
	v_mfma_f32_16x16x32_bf16 v[64:67], v[180:183], v[212:215], 0
	v_mfma_f32_16x16x32_bf16 v[108:111], v[176:179], v[192:195], v[108:111]
	v_mfma_f32_16x16x32_bf16 v[100:103], v[184:187], v[192:195], v[100:103]
	v_mfma_f32_16x16x32_bf16 v[92:95], v[176:179], v[200:203], v[92:95]
	v_mfma_f32_16x16x32_bf16 v[84:87], v[184:187], v[200:203], v[84:87]
	v_mfma_f32_16x16x32_bf16 v[76:79], v[176:179], v[208:211], v[76:79]
	v_mfma_f32_16x16x32_bf16 v[72:75], v[184:187], v[208:211], v[72:75]
	v_mfma_f32_16x16x32_bf16 v[68:71], v[176:179], v[216:219], v[68:71]
	v_mfma_f32_16x16x32_bf16 v[64:67], v[184:187], v[216:219], v[64:67]
	s_barrier
	s_add_i32 s57, s44, s31
	v_lshl_add_u64 v[220:221], s[22:23], 0, v[136:137]
	s_mov_b32 m0, s57
	ds_read_b128 v[188:191], v158 offset:16384
	ds_read_b128 v[192:195], v158 offset:17408
	ds_read_b128 v[196:199], v158 offset:18432
	ds_read_b128 v[200:203], v158 offset:19456
	ds_read_b128 v[204:207], v158 offset:20480
	ds_read_b128 v[208:211], v158 offset:21504
	ds_read_b128 v[212:215], v158 offset:22528
	ds_read_b128 v[216:219], v158 offset:23552
	global_load_lds_dwordx4 v[220:221], off
	v_lshl_add_u64 v[222:223], s[22:23], 0, v[130:131]
	s_add_i32 m0, s57, 0x2000
	s_add_i32 s57, s45, s31
	global_load_lds_dwordx4 v[222:223], off
	v_lshl_add_u64 v[224:225], s[22:23], 0, v[134:135]
	s_mov_b32 m0, s57
	v_lshl_add_u64 v[226:227], s[24:25], 0, v[132:133]
	global_load_lds_dwordx4 v[224:225], off
	v_lshl_add_u64 v[224:225], s[22:23], 0, v[128:129]
	s_add_i32 m0, s57, 0x2000
	s_nop 0
	global_load_lds_dwordx4 v[224:225], off
	v_lshl_add_u64 v[224:225], s[24:25], 0, v[138:139]
	s_mov_b32 m0, s35
	s_nop 0
	global_load_lds_dwordx4 v[224:225], off
	s_mov_b32 m0, s36
	s_nop 0
	global_load_lds_dwordx4 v[226:227], off
	s_waitcnt vmcnt(8)
	s_waitcnt lgkmcnt(0)
	s_barrier
; #define PG8_STAGE(bufoff, gbase, voff) do { _Pragma("unroll") for (int _i = 0; _i < 2; ++_i) \
;         __builtin_amdgcn_global_load_lds((const unsigned*)((const char*)(gbase) + (voff)[_i]), (LAS unsigned*)(lds + (bufoff) + ldsw + _i * 8192), 16, 0, 0); } while (0)
; #define PG8_LDA(dst, b, h) do { _Pragma("unroll") for (int m = 0; m < 4; ++m) _Pragma("unroll") for (int k = 0; k < 2; ++k) dst[m][k] = *(const LAS bf16x8*)(lds + PG8_SA(b, h) + aoff + m * 2048 + k * 1024); } while (0)
; #define PG8_LDB(dst, b, h) do { _Pragma("unroll") for (int n = 0; n < 2; ++n) _Pragma("unroll") for (int k = 0; k < 2; ++k) dst[n][k] = *(const LAS bf16x8*)(lds + PG8_SB(b, h) + boff + n * 2048 + k * 1024); } while (0)
; #define PG8_MMA(ai, bj, At, Bt) do { __builtin_amdgcn_s_setprio(1); _Pragma("unroll") for (int m = 0; m < 4; ++m) _Pragma("unroll") for (int n = 0; n < 2; ++n) _Pragma("unroll") for (int k = 0; k < 2; ++k) \
;         acc[ai][bj][m][n] = __builtin_amdgcn_mfma_f32_16x16x32_bf16(Bt[n][k], At[m][k], acc[ai][bj][m][n], 0, 0, 0); __builtin_amdgcn_s_setprio(0); } while (0)
; #define PG8_WAIT_V(n) asm volatile("s_waitcnt vmcnt(" #n ")" ::: "memory")
; #define PG8_WAIT_L(n) asm volatile("s_waitcnt lgkmcnt(" #n ")" ::: "memory")
; #define PG8_BAR __builtin_amdgcn_s_barrier()
; #define PG8_SCHED __builtin_amdgcn_sched_barrier(0)
; template <class Epi, class Sched>
; __device__ __forceinline__ void gemm_phase(LAS unsigned char* lds, const Sched& S, const Epi& E, bool natural = false) {
;     ...
;             PG8_WAIT_V(8); PG8_WAIT_L(0); PG8_BAR; PG8_MMA(1, 0, At, B0); PG8_MMA(1, 1, At, B1); PG8_BAR; PG8_SCHED;
;             PG8_LDB(B0, 1, 0); PG8_LDB(B1, 1, 1); PG8_SCHED; PG8_LDA(At, 1, 0); PG8_STAGE(PG8_SA(0, 1), a2 + hstep, voffA);
;             PG8_WAIT_V(8); PG8_WAIT_L(0); PG8_BAR; PG8_MMA(0, 0, At, B0); PG8_MMA(0, 1, At, B1); PG8_BAR; PG8_SCHED;
	s_waitcnt lgkmcnt(0)
	v_mfma_f32_16x16x32_bf16 v[60:63], v[150:153], v[188:191], 0
	v_mfma_f32_16x16x32_bf16 v[56:59], v[164:167], v[188:191], 0
	v_mfma_f32_16x16x32_bf16 v[52:55], v[150:153], v[196:199], 0
	v_mfma_f32_16x16x32_bf16 v[48:51], v[164:167], v[196:199], 0
	v_mfma_f32_16x16x32_bf16 v[44:47], v[150:153], v[204:207], 0
	v_mfma_f32_16x16x32_bf16 v[32:35], v[164:167], v[204:207], 0
	v_mfma_f32_16x16x32_bf16 v[20:23], v[150:153], v[212:215], 0
	v_mfma_f32_16x16x32_bf16 v[8:11], v[164:167], v[212:215], 0
	v_mfma_f32_16x16x32_bf16 v[60:63], v[160:163], v[192:195], v[60:63]
	v_mfma_f32_16x16x32_bf16 v[56:59], v[168:171], v[192:195], v[56:59]
	v_mfma_f32_16x16x32_bf16 v[52:55], v[160:163], v[200:203], v[52:55]
	v_mfma_f32_16x16x32_bf16 v[48:51], v[168:171], v[200:203], v[48:51]
	v_mfma_f32_16x16x32_bf16 v[44:47], v[160:163], v[208:211], v[44:47]
	v_mfma_f32_16x16x32_bf16 v[32:35], v[168:171], v[208:211], v[32:35]
	v_mfma_f32_16x16x32_bf16 v[20:23], v[160:163], v[216:219], v[20:23]
	v_mfma_f32_16x16x32_bf16 v[8:11], v[168:171], v[216:219], v[8:11]
	v_mfma_f32_16x16x32_bf16 v[40:43], v[172:175], v[188:191], 0
	v_mfma_f32_16x16x32_bf16 v[36:39], v[180:183], v[188:191], 0
	v_mfma_f32_16x16x32_bf16 v[28:31], v[172:175], v[196:199], 0
	v_mfma_f32_16x16x32_bf16 v[24:27], v[180:183], v[196:199], 0
	v_mfma_f32_16x16x32_bf16 v[16:19], v[172:175], v[204:207], 0
	v_mfma_f32_16x16x32_bf16 v[12:15], v[180:183], v[204:207], 0
	v_mfma_f32_16x16x32_bf16 v[4:7], v[172:175], v[212:215], 0
	v_mfma_f32_16x16x32_bf16 v[0:3], v[180:183], v[212:215], 0
	v_mfma_f32_16x16x32_bf16 v[40:43], v[176:179], v[192:195], v[40:43]
	v_mfma_f32_16x16x32_bf16 v[36:39], v[184:187], v[192:195], v[36:39]
	v_mfma_f32_16x16x32_bf16 v[28:31], v[176:179], v[200:203], v[28:31]
	v_mfma_f32_16x16x32_bf16 v[24:27], v[184:187], v[200:203], v[24:27]
	v_mfma_f32_16x16x32_bf16 v[16:19], v[176:179], v[208:211], v[16:19]
	v_mfma_f32_16x16x32_bf16 v[12:15], v[184:187], v[208:211], v[12:15]
	v_mfma_f32_16x16x32_bf16 v[4:7], v[176:179], v[216:219], v[4:7]
	v_mfma_f32_16x16x32_bf16 v[0:3], v[184:187], v[216:219], v[0:3]
	s_barrier
	s_add_i32 s57, 0, 0x18000
	v_add_u32_e32 v140, s57, v154
	s_add_i32 s58, 0, 0x1c000
	ds_read_b128 v[150:153], v140
	ds_read_b128 v[160:163], v140 offset:1024
	ds_read_b128 v[164:167], v140 offset:2048
	ds_read_b128 v[168:171], v140 offset:3072
	v_add_u32_e32 v140, s58, v154
	ds_read_b128 v[172:175], v140
	ds_read_b128 v[176:179], v140 offset:1024
	ds_read_b128 v[180:183], v140 offset:2048
	ds_read_b128 v[184:187], v140 offset:3072
	s_add_u32 s24, s24, 0x40000
	s_addc_u32 s25, s25, 0
	s_mov_b32 m0, s37
	v_lshl_add_u64 v[228:229], s[24:25], 0, v[138:139]
	ds_read_b128 v[188:191], v158 offset:32768
	ds_read_b128 v[192:195], v158 offset:33792
	ds_read_b128 v[196:199], v158 offset:34816
	ds_read_b128 v[200:203], v158 offset:35840
	ds_read_b128 v[204:207], v158 offset:36864
	ds_read_b128 v[208:211], v158 offset:37888
	ds_read_b128 v[212:215], v158 offset:38912
	ds_read_b128 v[216:219], v158 offset:39936
	global_load_lds_dwordx4 v[228:229], off
	v_lshl_add_u64 v[228:229], s[24:25], 0, v[132:133]
	s_mov_b32 m0, s38
	s_nop 0
	global_load_lds_dwordx4 v[228:229], off
	s_waitcnt vmcnt(8)
	s_waitcnt lgkmcnt(0)
	s_barrier
	s_waitcnt lgkmcnt(0)
	v_mfma_f32_16x16x32_bf16 v[124:127], v[150:153], v[188:191], v[124:127]
	v_mfma_f32_16x16x32_bf16 v[120:123], v[164:167], v[188:191], v[120:123]
	v_mfma_f32_16x16x32_bf16 v[116:119], v[150:153], v[196:199], v[116:119]
	v_mfma_f32_16x16x32_bf16 v[112:115], v[164:167], v[196:199], v[112:115]
	v_mfma_f32_16x16x32_bf16 v[104:107], v[150:153], v[204:207], v[104:107]
	v_mfma_f32_16x16x32_bf16 v[96:99], v[164:167], v[204:207], v[96:99]
	v_mfma_f32_16x16x32_bf16 v[88:91], v[150:153], v[212:215], v[88:91]
	v_mfma_f32_16x16x32_bf16 v[80:83], v[164:167], v[212:215], v[80:83]
	v_mfma_f32_16x16x32_bf16 v[124:127], v[160:163], v[192:195], v[124:127]
	v_mfma_f32_16x16x32_bf16 v[120:123], v[168:171], v[192:195], v[120:123]
	v_mfma_f32_16x16x32_bf16 v[116:119], v[160:163], v[200:203], v[116:119]
	v_mfma_f32_16x16x32_bf16 v[112:115], v[168:171], v[200:203], v[112:115]
	v_mfma_f32_16x16x32_bf16 v[104:107], v[160:163], v[208:211], v[104:107]
	v_mfma_f32_16x16x32_bf16 v[96:99], v[168:171], v[208:211], v[96:99]
	v_mfma_f32_16x16x32_bf16 v[88:91], v[160:163], v[216:219], v[88:91]
	v_mfma_f32_16x16x32_bf16 v[80:83], v[168:171], v[216:219], v[80:83]
	v_mfma_f32_16x16x32_bf16 v[108:111], v[172:175], v[188:191], v[108:111]
	v_mfma_f32_16x16x32_bf16 v[100:103], v[180:183], v[188:191], v[100:103]
	v_mfma_f32_16x16x32_bf16 v[92:95], v[172:175], v[196:199], v[92:95]
	v_mfma_f32_16x16x32_bf16 v[84:87], v[180:183], v[196:199], v[84:87]
	v_mfma_f32_16x16x32_bf16 v[76:79], v[172:175], v[204:207], v[76:79]
	v_mfma_f32_16x16x32_bf16 v[72:75], v[180:183], v[204:207], v[72:75]
	v_mfma_f32_16x16x32_bf16 v[68:71], v[172:175], v[212:215], v[68:71]
	v_mfma_f32_16x16x32_bf16 v[64:67], v[180:183], v[212:215], v[64:67]
	v_mfma_f32_16x16x32_bf16 v[108:111], v[176:179], v[192:195], v[108:111]
	v_mfma_f32_16x16x32_bf16 v[100:103], v[184:187], v[192:195], v[100:103]
	v_mfma_f32_16x16x32_bf16 v[92:95], v[176:179], v[200:203], v[92:95]
	v_mfma_f32_16x16x32_bf16 v[84:87], v[184:187], v[200:203], v[84:87]
	v_mfma_f32_16x16x32_bf16 v[76:79], v[176:179], v[208:211], v[76:79]
	v_mfma_f32_16x16x32_bf16 v[72:75], v[184:187], v[208:211], v[72:75]
	v_mfma_f32_16x16x32_bf16 v[68:71], v[176:179], v[216:219], v[68:71]
	v_mfma_f32_16x16x32_bf16 v[64:67], v[184:187], v[216:219], v[64:67]
	s_barrier
; #define PG8_STAGE(bufoff, gbase, voff) do { _Pragma("unroll") for (int _i = 0; _i < 2; ++_i) \
;         __builtin_amdgcn_global_load_lds((const unsigned*)((const char*)(gbase) + (voff)[_i]), (LAS unsigned*)(lds + (bufoff) + ldsw + _i * 8192), 16, 0, 0); } while (0)
; #define PG8_LDA(dst, b, h) do { _Pragma("unroll") for (int m = 0; m < 4; ++m) _Pragma("unroll") for (int k = 0; k < 2; ++k) dst[m][k] = *(const LAS bf16x8*)(lds + PG8_SA(b, h) + aoff + m * 2048 + k * 1024); } while (0)
; #define PG8_LDB(dst, b, h) do { _Pragma("unroll") for (int n = 0; n < 2; ++n) _Pragma("unroll") for (int k = 0; k < 2; ++k) dst[n][k] = *(const LAS bf16x8*)(lds + PG8_SB(b, h) + boff + n * 2048 + k * 1024); } while (0)
; #define PG8_MMA(ai, bj, At, Bt) do { __builtin_amdgcn_s_setprio(1); _Pragma("unroll") for (int m = 0; m < 4; ++m) _Pragma("unroll") for (int n = 0; n < 2; ++n) _Pragma("unroll") for (int k = 0; k < 2; ++k) \
;         acc[ai][bj][m][n] = __builtin_amdgcn_mfma_f32_16x16x32_bf16(Bt[n][k], At[m][k], acc[ai][bj][m][n], 0, 0, 0); __builtin_amdgcn_s_setprio(0); } while (0)
; #define PG8_WAIT_V(n) asm volatile("s_waitcnt vmcnt(" #n ")" ::: "memory")
; #define PG8_WAIT_L(n) asm volatile("s_waitcnt lgkmcnt(" #n ")" ::: "memory")
; #define PG8_BAR __builtin_amdgcn_s_barrier()
; #define PG8_SCHED __builtin_amdgcn_sched_barrier(0)
; template <class Epi, class Sched>
; __device__ __forceinline__ void gemm_phase(LAS unsigned char* lds, const Sched& S, const Epi& E, bool natural = false) {
;     ...
;             PG8_LDB(B0, 0, 0); PG8_LDB(B1, 0, 1); PG8_SCHED; PG8_LDA(At, 0, 0); PG8_STAGE(PG8_SA(1, 1), a1 + hstep, voffA);
;             PG8_WAIT_V(8); PG8_WAIT_L(0); PG8_BAR; PG8_MMA(0, 0, At, B0); PG8_MMA(0, 1, At, B1); PG8_BAR; PG8_SCHED;
;     ...
;             PG8_LDA(At, 1, 1); PG8_STAGE(PG8_SB(1, 0), b3, voffB0); PG8_STAGE(PG8_SB(1, 1), b3, voffB1); PG8_STAGE(PG8_SA(1, 0), a3, voffA);
;             PG8_WAIT_V(8); PG8_WAIT_L(0); PG8_BAR; PG8_MMA(1, 0, At, B0); PG8_MMA(1, 1, At, B1); PG8_BAR; PG8_SCHED;
;         }
	s_add_u32 s22, s22, 0x80
	s_addc_u32 s23, s23, 0
	s_add_i32 s24, s57, s31
	v_lshl_add_u64 v[220:221], v[220:221], 0, s[8:9]
	s_mov_b32 m0, s24
	ds_read_b128 v[188:191], v158 offset:49152
	ds_read_b128 v[192:195], v158 offset:50176
	ds_read_b128 v[196:199], v158 offset:51200
	ds_read_b128 v[200:203], v158 offset:52224
	ds_read_b128 v[204:207], v158 offset:53248
	ds_read_b128 v[208:211], v158 offset:54272
	ds_read_b128 v[212:215], v158 offset:55296
	ds_read_b128 v[216:219], v158 offset:56320
	global_load_lds_dwordx4 v[220:221], off
	v_lshl_add_u64 v[220:221], v[222:223], 0, s[8:9]
	s_add_i32 m0, s24, 0x2000
	s_add_i32 s24, s58, s31
	global_load_lds_dwordx4 v[220:221], off
	v_lshl_add_u64 v[220:221], s[22:23], 0, v[134:135]
	s_mov_b32 m0, s24
	s_nop 0
	global_load_lds_dwordx4 v[220:221], off
	v_lshl_add_u64 v[220:221], s[22:23], 0, v[128:129]
	s_add_i32 m0, s24, 0x2000
	s_nop 0
	global_load_lds_dwordx4 v[220:221], off
	v_lshl_add_u64 v[220:221], v[224:225], 0, s[8:9]
	s_mov_b32 m0, s41
	s_nop 0
	global_load_lds_dwordx4 v[220:221], off
	v_lshl_add_u64 v[220:221], v[226:227], 0, s[8:9]
	s_mov_b32 m0, s42
	s_nop 0
	global_load_lds_dwordx4 v[220:221], off
	s_waitcnt vmcnt(8)
	s_waitcnt lgkmcnt(0)
	s_barrier
	s_waitcnt lgkmcnt(0)
	v_mfma_f32_16x16x32_bf16 v[60:63], v[150:153], v[188:191], v[60:63]
	v_mfma_f32_16x16x32_bf16 v[56:59], v[164:167], v[188:191], v[56:59]
	v_mfma_f32_16x16x32_bf16 v[52:55], v[150:153], v[196:199], v[52:55]
	v_mfma_f32_16x16x32_bf16 v[48:51], v[164:167], v[196:199], v[48:51]
	v_mfma_f32_16x16x32_bf16 v[44:47], v[150:153], v[204:207], v[44:47]
	v_mfma_f32_16x16x32_bf16 v[32:35], v[164:167], v[204:207], v[32:35]
	v_mfma_f32_16x16x32_bf16 v[20:23], v[150:153], v[212:215], v[20:23]
	v_mfma_f32_16x16x32_bf16 v[8:11], v[164:167], v[212:215], v[8:11]
	v_mfma_f32_16x16x32_bf16 v[60:63], v[160:163], v[192:195], v[60:63]
	v_mfma_f32_16x16x32_bf16 v[56:59], v[168:171], v[192:195], v[56:59]
	v_mfma_f32_16x16x32_bf16 v[52:55], v[160:163], v[200:203], v[52:55]
	v_mfma_f32_16x16x32_bf16 v[48:51], v[168:171], v[200:203], v[48:51]
	v_mfma_f32_16x16x32_bf16 v[44:47], v[160:163], v[208:211], v[44:47]
	v_mfma_f32_16x16x32_bf16 v[32:35], v[168:171], v[208:211], v[32:35]
	v_mfma_f32_16x16x32_bf16 v[20:23], v[160:163], v[216:219], v[20:23]
	v_mfma_f32_16x16x32_bf16 v[8:11], v[168:171], v[216:219], v[8:11]
	v_mfma_f32_16x16x32_bf16 v[40:43], v[172:175], v[188:191], v[40:43]
	v_mfma_f32_16x16x32_bf16 v[36:39], v[180:183], v[188:191], v[36:39]
	v_mfma_f32_16x16x32_bf16 v[28:31], v[172:175], v[196:199], v[28:31]
	v_mfma_f32_16x16x32_bf16 v[24:27], v[180:183], v[196:199], v[24:27]
	v_mfma_f32_16x16x32_bf16 v[16:19], v[172:175], v[204:207], v[16:19]
	v_mfma_f32_16x16x32_bf16 v[12:15], v[180:183], v[204:207], v[12:15]
	v_mfma_f32_16x16x32_bf16 v[4:7], v[172:175], v[212:215], v[4:7]
	v_mfma_f32_16x16x32_bf16 v[0:3], v[180:183], v[212:215], v[0:3]
	v_mfma_f32_16x16x32_bf16 v[40:43], v[176:179], v[192:195], v[40:43]
	v_mfma_f32_16x16x32_bf16 v[36:39], v[184:187], v[192:195], v[36:39]
	v_mfma_f32_16x16x32_bf16 v[28:31], v[176:179], v[200:203], v[28:31]
	v_mfma_f32_16x16x32_bf16 v[24:27], v[184:187], v[200:203], v[24:27]
	v_mfma_f32_16x16x32_bf16 v[16:19], v[176:179], v[208:211], v[16:19]
	v_mfma_f32_16x16x32_bf16 v[12:15], v[184:187], v[208:211], v[12:15]
	v_mfma_f32_16x16x32_bf16 v[4:7], v[176:179], v[216:219], v[4:7]
	v_mfma_f32_16x16x32_bf16 v[0:3], v[184:187], v[216:219], v[0:3]
	s_barrier
	s_add_i32 s56, s56, 2
	s_add_u32 s20, s20, 0x100
	s_addc_u32 s21, s21, 0
	s_add_u32 s54, s54, 0x100
	s_addc_u32 s55, s55, 0
	s_cmp_gt_u32 s56, 13
	s_cbranch_scc0 .LBB0_564
.LBB0_564:
	ds_read_b128 v[150:153], v156
	ds_read_b128 v[160:163], v156 offset:1024
	ds_read_b128 v[164:167], v156 offset:2048
	ds_read_b128 v[168:171], v156 offset:3072
	ds_read_b128 v[172:175], v157
	ds_read_b128 v[176:179], v157 offset:1024
	ds_read_b128 v[180:183], v157 offset:2048
	ds_read_b128 v[184:187], v157 offset:3072
	s_add_u32 s22, s20, 0xfffc0080
	s_addc_u32 s23, s21, -1
	s_cmp_eq_u32 s56, 12
	s_cselect_b32 s25, s13, s23
	s_cselect_b32 s24, s15, s22
	s_cselect_b32 s23, s26, s55
	s_cselect_b32 s22, s27, s54
	v_lshl_add_u64 v[220:221], s[20:21], 0, v[142:143]
	s_add_i32 m0, s35, 0xc000
	ds_read_b128 v[188:191], v158
	ds_read_b128 v[192:195], v158 offset:1024
	ds_read_b128 v[196:199], v158 offset:2048
	ds_read_b128 v[200:203], v158 offset:3072
	ds_read_b128 v[204:207], v158 offset:4096
	ds_read_b128 v[208:211], v158 offset:5120
	ds_read_b128 v[212:215], v158 offset:6144
	ds_read_b128 v[216:219], v158 offset:7168
	global_load_lds_dwordx4 v[220:221], off
	v_lshl_add_u64 v[220:221], s[20:21], 0, v[144:145]
	s_add_i32 m0, s35, 0xe000
	s_nop 0
	global_load_lds_dwordx4 v[220:221], off
	s_waitcnt vmcnt(8)
	s_waitcnt lgkmcnt(0)
	s_barrier
; #define PG8_STAGE(bufoff, gbase, voff) do { _Pragma("unroll") for (int _i = 0; _i < 2; ++_i) \
;         __builtin_amdgcn_global_load_lds((const unsigned*)((const char*)(gbase) + (voff)[_i]), (LAS unsigned*)(lds + (bufoff) + ldsw + _i * 8192), 16, 0, 0); } while (0)
; #define PG8_LDA(dst, b, h) do { _Pragma("unroll") for (int m = 0; m < 4; ++m) _Pragma("unroll") for (int k = 0; k < 2; ++k) dst[m][k] = *(const LAS bf16x8*)(lds + PG8_SA(b, h) + aoff + m * 2048 + k * 1024); } while (0)
; #define PG8_MMA(ai, bj, At, Bt) do { __builtin_amdgcn_s_setprio(1); _Pragma("unroll") for (int m = 0; m < 4; ++m) _Pragma("unroll") for (int n = 0; n < 2; ++n) _Pragma("unroll") for (int k = 0; k < 2; ++k) \
;         acc[ai][bj][m][n] = __builtin_amdgcn_mfma_f32_16x16x32_bf16(Bt[n][k], At[m][k], acc[ai][bj][m][n], 0, 0, 0); __builtin_amdgcn_s_setprio(0); } while (0)
; #define PG8_WAIT_V(n) asm volatile("s_waitcnt vmcnt(" #n ")" ::: "memory")
; #define PG8_WAIT_L(n) asm volatile("s_waitcnt lgkmcnt(" #n ")" ::: "memory")
; #define PG8_BAR __builtin_amdgcn_s_barrier()
; #define PG8_SCHED __builtin_amdgcn_sched_barrier(0)
; template <class Epi, class Sched>
; __device__ __forceinline__ void gemm_phase(LAS unsigned char* lds, const Sched& S, const Epi& E, bool natural = false) {
;     ...
;             PG8_WAIT_V(8); PG8_WAIT_L(0); PG8_BAR; PG8_MMA(0, 0, At, B0); PG8_MMA(0, 1, At, B1); PG8_BAR; PG8_SCHED;
;             PG8_LDA(At, 0, 1); PG8_STAGE(PG8_SB(0, 0), b2, voffB0); PG8_STAGE(PG8_SB(0, 1), b2, voffB1); PG8_STAGE(PG8_SA(0, 0), a2, voffA);
;             PG8_WAIT_V(8); PG8_WAIT_L(0); PG8_BAR; PG8_MMA(1, 0, At, B0); PG8_MMA(1, 1, At, B1); PG8_BAR; PG8_SCHED;
	s_waitcnt lgkmcnt(0)
	v_mfma_f32_16x16x32_bf16 v[124:127], v[150:153], v[188:191], v[124:127]
	v_mfma_f32_16x16x32_bf16 v[120:123], v[164:167], v[188:191], v[120:123]
	v_mfma_f32_16x16x32_bf16 v[116:119], v[150:153], v[196:199], v[116:119]
	v_mfma_f32_16x16x32_bf16 v[112:115], v[164:167], v[196:199], v[112:115]
	v_mfma_f32_16x16x32_bf16 v[104:107], v[150:153], v[204:207], v[104:107]
	v_mfma_f32_16x16x32_bf16 v[96:99], v[164:167], v[204:207], v[96:99]
	v_mfma_f32_16x16x32_bf16 v[88:91], v[150:153], v[212:215], v[88:91]
	v_mfma_f32_16x16x32_bf16 v[80:83], v[164:167], v[212:215], v[80:83]
	v_mfma_f32_16x16x32_bf16 v[124:127], v[160:163], v[192:195], v[124:127]
	v_mfma_f32_16x16x32_bf16 v[120:123], v[168:171], v[192:195], v[120:123]
	v_mfma_f32_16x16x32_bf16 v[116:119], v[160:163], v[200:203], v[116:119]
	v_mfma_f32_16x16x32_bf16 v[112:115], v[168:171], v[200:203], v[112:115]
	v_mfma_f32_16x16x32_bf16 v[104:107], v[160:163], v[208:211], v[104:107]
	v_mfma_f32_16x16x32_bf16 v[96:99], v[168:171], v[208:211], v[96:99]
	v_mfma_f32_16x16x32_bf16 v[88:91], v[160:163], v[216:219], v[88:91]
	v_mfma_f32_16x16x32_bf16 v[80:83], v[168:171], v[216:219], v[80:83]
	v_mfma_f32_16x16x32_bf16 v[108:111], v[172:175], v[188:191], v[108:111]
	v_mfma_f32_16x16x32_bf16 v[100:103], v[180:183], v[188:191], v[100:103]
	v_mfma_f32_16x16x32_bf16 v[92:95], v[172:175], v[196:199], v[92:95]
	v_mfma_f32_16x16x32_bf16 v[84:87], v[180:183], v[196:199], v[84:87]
	v_mfma_f32_16x16x32_bf16 v[76:79], v[172:175], v[204:207], v[76:79]
	v_mfma_f32_16x16x32_bf16 v[72:75], v[180:183], v[204:207], v[72:75]
	v_mfma_f32_16x16x32_bf16 v[68:71], v[172:175], v[212:215], v[68:71]
	v_mfma_f32_16x16x32_bf16 v[64:67], v[180:183], v[212:215], v[64:67]
	v_mfma_f32_16x16x32_bf16 v[108:111], v[176:179], v[192:195], v[108:111]
	v_mfma_f32_16x16x32_bf16 v[100:103], v[184:187], v[192:195], v[100:103]
	v_mfma_f32_16x16x32_bf16 v[92:95], v[176:179], v[200:203], v[92:95]
	v_mfma_f32_16x16x32_bf16 v[84:87], v[184:187], v[200:203], v[84:87]
	v_mfma_f32_16x16x32_bf16 v[76:79], v[176:179], v[208:211], v[76:79]
	v_mfma_f32_16x16x32_bf16 v[72:75], v[184:187], v[208:211], v[72:75]
	v_mfma_f32_16x16x32_bf16 v[68:71], v[176:179], v[216:219], v[68:71]
	v_mfma_f32_16x16x32_bf16 v[64:67], v[184:187], v[216:219], v[64:67]
	s_barrier
	s_add_i32 s57, s44, s31
	v_lshl_add_u64 v[220:221], s[22:23], 0, v[136:137]
	s_mov_b32 m0, s57
	ds_read_b128 v[188:191], v158 offset:16384
	ds_read_b128 v[192:195], v158 offset:17408
	ds_read_b128 v[196:199], v158 offset:18432
	ds_read_b128 v[200:203], v158 offset:19456
	ds_read_b128 v[204:207], v158 offset:20480
	ds_read_b128 v[208:211], v158 offset:21504
	ds_read_b128 v[212:215], v158 offset:22528
	ds_read_b128 v[216:219], v158 offset:23552
	global_load_lds_dwordx4 v[220:221], off
	v_lshl_add_u64 v[222:223], s[22:23], 0, v[130:131]
	s_add_i32 m0, s57, 0x2000
	s_add_i32 s57, s45, s31
	global_load_lds_dwordx4 v[222:223], off
	v_lshl_add_u64 v[224:225], s[22:23], 0, v[134:135]
	s_mov_b32 m0, s57
	v_lshl_add_u64 v[226:227], s[24:25], 0, v[132:133]
	global_load_lds_dwordx4 v[224:225], off
	v_lshl_add_u64 v[224:225], s[22:23], 0, v[128:129]
	s_add_i32 m0, s57, 0x2000
	s_nop 0
	global_load_lds_dwordx4 v[224:225], off
	v_lshl_add_u64 v[224:225], s[24:25], 0, v[138:139]
	s_mov_b32 m0, s35
	s_nop 0
	global_load_lds_dwordx4 v[224:225], off
	s_mov_b32 m0, s36
	s_nop 0
	global_load_lds_dwordx4 v[226:227], off
	s_waitcnt vmcnt(8)
	s_waitcnt lgkmcnt(0)
	s_barrier
	s_waitcnt lgkmcnt(0)
	v_mfma_f32_16x16x32_bf16 v[60:63], v[150:153], v[188:191], v[60:63]
	v_mfma_f32_16x16x32_bf16 v[56:59], v[164:167], v[188:191], v[56:59]
	v_mfma_f32_16x16x32_bf16 v[52:55], v[150:153], v[196:199], v[52:55]
	v_mfma_f32_16x16x32_bf16 v[48:51], v[164:167], v[196:199], v[48:51]
	v_mfma_f32_16x16x32_bf16 v[44:47], v[150:153], v[204:207], v[44:47]
	v_mfma_f32_16x16x32_bf16 v[32:35], v[164:167], v[204:207], v[32:35]
	v_mfma_f32_16x16x32_bf16 v[20:23], v[150:153], v[212:215], v[20:23]
	v_mfma_f32_16x16x32_bf16 v[8:11], v[164:167], v[212:215], v[8:11]
	v_mfma_f32_16x16x32_bf16 v[60:63], v[160:163], v[192:195], v[60:63]
	v_mfma_f32_16x16x32_bf16 v[56:59], v[168:171], v[192:195], v[56:59]
	v_mfma_f32_16x16x32_bf16 v[52:55], v[160:163], v[200:203], v[52:55]
	v_mfma_f32_16x16x32_bf16 v[48:51], v[168:171], v[200:203], v[48:51]
	v_mfma_f32_16x16x32_bf16 v[44:47], v[160:163], v[208:211], v[44:47]
	v_mfma_f32_16x16x32_bf16 v[32:35], v[168:171], v[208:211], v[32:35]
	v_mfma_f32_16x16x32_bf16 v[20:23], v[160:163], v[216:219], v[20:23]
	v_mfma_f32_16x16x32_bf16 v[8:11], v[168:171], v[216:219], v[8:11]
	v_mfma_f32_16x16x32_bf16 v[40:43], v[172:175], v[188:191], v[40:43]
	v_mfma_f32_16x16x32_bf16 v[36:39], v[180:183], v[188:191], v[36:39]
	v_mfma_f32_16x16x32_bf16 v[28:31], v[172:175], v[196:199], v[28:31]
	v_mfma_f32_16x16x32_bf16 v[24:27], v[180:183], v[196:199], v[24:27]
	v_mfma_f32_16x16x32_bf16 v[16:19], v[172:175], v[204:207], v[16:19]
	v_mfma_f32_16x16x32_bf16 v[12:15], v[180:183], v[204:207], v[12:15]
	v_mfma_f32_16x16x32_bf16 v[4:7], v[172:175], v[212:215], v[4:7]
	v_mfma_f32_16x16x32_bf16 v[0:3], v[180:183], v[212:215], v[0:3]
	v_mfma_f32_16x16x32_bf16 v[40:43], v[176:179], v[192:195], v[40:43]
	v_mfma_f32_16x16x32_bf16 v[36:39], v[184:187], v[192:195], v[36:39]
	v_mfma_f32_16x16x32_bf16 v[28:31], v[176:179], v[200:203], v[28:31]
	v_mfma_f32_16x16x32_bf16 v[24:27], v[184:187], v[200:203], v[24:27]
	v_mfma_f32_16x16x32_bf16 v[16:19], v[176:179], v[208:211], v[16:19]
	v_mfma_f32_16x16x32_bf16 v[12:15], v[184:187], v[208:211], v[12:15]
	v_mfma_f32_16x16x32_bf16 v[4:7], v[176:179], v[216:219], v[4:7]
	v_mfma_f32_16x16x32_bf16 v[0:3], v[184:187], v[216:219], v[0:3]
	s_barrier
; #define PG8_STAGE(bufoff, gbase, voff) do { _Pragma("unroll") for (int _i = 0; _i < 2; ++_i) \
;         __builtin_amdgcn_global_load_lds((const unsigned*)((const char*)(gbase) + (voff)[_i]), (LAS unsigned*)(lds + (bufoff) + ldsw + _i * 8192), 16, 0, 0); } while (0)
; #define PG8_LDA(dst, b, h) do { _Pragma("unroll") for (int m = 0; m < 4; ++m) _Pragma("unroll") for (int k = 0; k < 2; ++k) dst[m][k] = *(const LAS bf16x8*)(lds + PG8_SA(b, h) + aoff + m * 2048 + k * 1024); } while (0)
; #define PG8_LDB(dst, b, h) do { _Pragma("unroll") for (int n = 0; n < 2; ++n) _Pragma("unroll") for (int k = 0; k < 2; ++k) dst[n][k] = *(const LAS bf16x8*)(lds + PG8_SB(b, h) + boff + n * 2048 + k * 1024); } while (0)
; #define PG8_MMA(ai, bj, At, Bt) do { __builtin_amdgcn_s_setprio(1); _Pragma("unroll") for (int m = 0; m < 4; ++m) _Pragma("unroll") for (int n = 0; n < 2; ++n) _Pragma("unroll") for (int k = 0; k < 2; ++k) \
;         acc[ai][bj][m][n] = __builtin_amdgcn_mfma_f32_16x16x32_bf16(Bt[n][k], At[m][k], acc[ai][bj][m][n], 0, 0, 0); __builtin_amdgcn_s_setprio(0); } while (0)
; #define PG8_WAIT_V(n) asm volatile("s_waitcnt vmcnt(" #n ")" ::: "memory")
; #define PG8_WAIT_L(n) asm volatile("s_waitcnt lgkmcnt(" #n ")" ::: "memory")
; #define PG8_BAR __builtin_amdgcn_s_barrier()
; #define PG8_SCHED __builtin_amdgcn_sched_barrier(0)
; template <class Epi, class Sched>
; __device__ __forceinline__ void gemm_phase(LAS unsigned char* lds, const Sched& S, const Epi& E, bool natural = false) {
;     ...
;             PG8_LDB(B0, 1, 0); PG8_LDB(B1, 1, 1); PG8_SCHED; PG8_LDA(At, 1, 0); PG8_STAGE(PG8_SA(0, 1), a2 + hstep, voffA);
;             PG8_WAIT_V(8); PG8_WAIT_L(0); PG8_BAR; PG8_MMA(0, 0, At, B0); PG8_MMA(0, 1, At, B1); PG8_BAR; PG8_SCHED;
	s_add_i32 s57, 0, 0x18000
	v_add_u32_e32 v140, s57, v154
	s_add_i32 s58, 0, 0x1c000
	ds_read_b128 v[150:153], v140
	ds_read_b128 v[160:163], v140 offset:1024
	ds_read_b128 v[164:167], v140 offset:2048
	ds_read_b128 v[168:171], v140 offset:3072
	v_add_u32_e32 v140, s58, v154
	ds_read_b128 v[172:175], v140
	ds_read_b128 v[176:179], v140 offset:1024
	ds_read_b128 v[180:183], v140 offset:2048
	ds_read_b128 v[184:187], v140 offset:3072
	s_add_u32 s24, s24, 0x40000
	s_addc_u32 s25, s25, 0
	s_mov_b32 m0, s37
	v_lshl_add_u64 v[228:229], s[24:25], 0, v[138:139]
	ds_read_b128 v[188:191], v158 offset:32768
	ds_read_b128 v[192:195], v158 offset:33792
	ds_read_b128 v[196:199], v158 offset:34816
	ds_read_b128 v[200:203], v158 offset:35840
	ds_read_b128 v[204:207], v158 offset:36864
	ds_read_b128 v[208:211], v158 offset:37888
	ds_read_b128 v[212:215], v158 offset:38912
	ds_read_b128 v[216:219], v158 offset:39936
	global_load_lds_dwordx4 v[228:229], off
	v_lshl_add_u64 v[228:229], s[24:25], 0, v[132:133]
	s_mov_b32 m0, s38
	s_nop 0
	global_load_lds_dwordx4 v[228:229], off
	s_waitcnt vmcnt(8)
	s_waitcnt lgkmcnt(0)
	s_barrier
	s_waitcnt lgkmcnt(0)
	v_mfma_f32_16x16x32_bf16 v[124:127], v[150:153], v[188:191], v[124:127]
	v_mfma_f32_16x16x32_bf16 v[120:123], v[164:167], v[188:191], v[120:123]
	v_mfma_f32_16x16x32_bf16 v[116:119], v[150:153], v[196:199], v[116:119]
	v_mfma_f32_16x16x32_bf16 v[112:115], v[164:167], v[196:199], v[112:115]
	v_mfma_f32_16x16x32_bf16 v[104:107], v[150:153], v[204:207], v[104:107]
	v_mfma_f32_16x16x32_bf16 v[96:99], v[164:167], v[204:207], v[96:99]
	v_mfma_f32_16x16x32_bf16 v[88:91], v[150:153], v[212:215], v[88:91]
	v_mfma_f32_16x16x32_bf16 v[80:83], v[164:167], v[212:215], v[80:83]
	v_mfma_f32_16x16x32_bf16 v[124:127], v[160:163], v[192:195], v[124:127]
	v_mfma_f32_16x16x32_bf16 v[120:123], v[168:171], v[192:195], v[120:123]
	v_mfma_f32_16x16x32_bf16 v[116:119], v[160:163], v[200:203], v[116:119]
	v_mfma_f32_16x16x32_bf16 v[112:115], v[168:171], v[200:203], v[112:115]
	v_mfma_f32_16x16x32_bf16 v[104:107], v[160:163], v[208:211], v[104:107]
	v_mfma_f32_16x16x32_bf16 v[96:99], v[168:171], v[208:211], v[96:99]
	v_mfma_f32_16x16x32_bf16 v[88:91], v[160:163], v[216:219], v[88:91]
	v_mfma_f32_16x16x32_bf16 v[80:83], v[168:171], v[216:219], v[80:83]
	v_mfma_f32_16x16x32_bf16 v[108:111], v[172:175], v[188:191], v[108:111]
	v_mfma_f32_16x16x32_bf16 v[100:103], v[180:183], v[188:191], v[100:103]
	v_mfma_f32_16x16x32_bf16 v[92:95], v[172:175], v[196:199], v[92:95]
	v_mfma_f32_16x16x32_bf16 v[84:87], v[180:183], v[196:199], v[84:87]
	v_mfma_f32_16x16x32_bf16 v[76:79], v[172:175], v[204:207], v[76:79]
	v_mfma_f32_16x16x32_bf16 v[72:75], v[180:183], v[204:207], v[72:75]
	v_mfma_f32_16x16x32_bf16 v[68:71], v[172:175], v[212:215], v[68:71]
	v_mfma_f32_16x16x32_bf16 v[64:67], v[180:183], v[212:215], v[64:67]
	v_mfma_f32_16x16x32_bf16 v[108:111], v[176:179], v[192:195], v[108:111]
	v_mfma_f32_16x16x32_bf16 v[100:103], v[184:187], v[192:195], v[100:103]
	v_mfma_f32_16x16x32_bf16 v[92:95], v[176:179], v[200:203], v[92:95]
	v_mfma_f32_16x16x32_bf16 v[84:87], v[184:187], v[200:203], v[84:87]
	v_mfma_f32_16x16x32_bf16 v[76:79], v[176:179], v[208:211], v[76:79]
	v_mfma_f32_16x16x32_bf16 v[72:75], v[184:187], v[208:211], v[72:75]
	v_mfma_f32_16x16x32_bf16 v[68:71], v[176:179], v[216:219], v[68:71]
	v_mfma_f32_16x16x32_bf16 v[64:67], v[184:187], v[216:219], v[64:67]
	s_barrier
; #define PG8_STAGE(bufoff, gbase, voff) do { _Pragma("unroll") for (int _i = 0; _i < 2; ++_i) \
;         __builtin_amdgcn_global_load_lds((const unsigned*)((const char*)(gbase) + (voff)[_i]), (LAS unsigned*)(lds + (bufoff) + ldsw + _i * 8192), 16, 0, 0); } while (0)
; #define PG8_LDA(dst, b, h) do { _Pragma("unroll") for (int m = 0; m < 4; ++m) _Pragma("unroll") for (int k = 0; k < 2; ++k) dst[m][k] = *(const LAS bf16x8*)(lds + PG8_SA(b, h) + aoff + m * 2048 + k * 1024); } while (0)
; #define PG8_MMA(ai, bj, At, Bt) do { __builtin_amdgcn_s_setprio(1); _Pragma("unroll") for (int m = 0; m < 4; ++m) _Pragma("unroll") for (int n = 0; n < 2; ++n) _Pragma("unroll") for (int k = 0; k < 2; ++k) \
;         acc[ai][bj][m][n] = __builtin_amdgcn_mfma_f32_16x16x32_bf16(Bt[n][k], At[m][k], acc[ai][bj][m][n], 0, 0, 0); __builtin_amdgcn_s_setprio(0); } while (0)
; #define PG8_WAIT_V(n) asm volatile("s_waitcnt vmcnt(" #n ")" ::: "memory")
; #define PG8_WAIT_L(n) asm volatile("s_waitcnt lgkmcnt(" #n ")" ::: "memory")
; #define PG8_BAR __builtin_amdgcn_s_barrier()
; #define PG8_SCHED __builtin_amdgcn_sched_barrier(0)
; template <class Epi, class Sched>
; __device__ __forceinline__ void gemm_phase(LAS unsigned char* lds, const Sched& S, const Epi& E, bool natural = false) {
;     ...
;             PG8_LDA(At, 1, 1); PG8_STAGE(PG8_SB(1, 0), b3, voffB0); PG8_STAGE(PG8_SB(1, 1), b3, voffB1); PG8_STAGE(PG8_SA(1, 0), a3, voffA);
;             PG8_WAIT_V(8); PG8_WAIT_L(0); PG8_BAR; PG8_MMA(1, 0, At, B0); PG8_MMA(1, 1, At, B1); PG8_BAR; PG8_SCHED;
;         }
;         if (wr == 0) PG8_BAR;
	s_add_u32 s22, s22, 0x80
	s_addc_u32 s23, s23, 0
	s_add_i32 s24, s57, s31
	v_lshl_add_u64 v[220:221], v[220:221], 0, s[8:9]
	s_mov_b32 m0, s24
	ds_read_b128 v[188:191], v158 offset:49152
	ds_read_b128 v[192:195], v158 offset:50176
	ds_read_b128 v[196:199], v158 offset:51200
	ds_read_b128 v[200:203], v158 offset:52224
	ds_read_b128 v[204:207], v158 offset:53248
	ds_read_b128 v[208:211], v158 offset:54272
	ds_read_b128 v[212:215], v158 offset:55296
	ds_read_b128 v[216:219], v158 offset:56320
	global_load_lds_dwordx4 v[220:221], off
	v_lshl_add_u64 v[220:221], v[222:223], 0, s[8:9]
	s_add_i32 m0, s24, 0x2000
	s_add_i32 s24, s58, s31
	global_load_lds_dwordx4 v[220:221], off
	v_lshl_add_u64 v[220:221], s[22:23], 0, v[134:135]
	s_mov_b32 m0, s24
	s_nop 0
	global_load_lds_dwordx4 v[220:221], off
	v_lshl_add_u64 v[220:221], s[22:23], 0, v[128:129]
	s_add_i32 m0, s24, 0x2000
	s_nop 0
	global_load_lds_dwordx4 v[220:221], off
	v_lshl_add_u64 v[220:221], v[224:225], 0, s[8:9]
	s_mov_b32 m0, s41
	s_nop 0
	global_load_lds_dwordx4 v[220:221], off
	v_lshl_add_u64 v[220:221], v[226:227], 0, s[8:9]
	s_mov_b32 m0, s42
	s_nop 0
	global_load_lds_dwordx4 v[220:221], off
	s_waitcnt vmcnt(8)
	s_waitcnt lgkmcnt(0)
	s_barrier
	s_waitcnt lgkmcnt(0)
	v_mfma_f32_16x16x32_bf16 v[60:63], v[150:153], v[188:191], v[60:63]
	v_mfma_f32_16x16x32_bf16 v[56:59], v[164:167], v[188:191], v[56:59]
	v_mfma_f32_16x16x32_bf16 v[52:55], v[150:153], v[196:199], v[52:55]
	v_mfma_f32_16x16x32_bf16 v[48:51], v[164:167], v[196:199], v[48:51]
	v_mfma_f32_16x16x32_bf16 v[44:47], v[150:153], v[204:207], v[44:47]
	v_mfma_f32_16x16x32_bf16 v[32:35], v[164:167], v[204:207], v[32:35]
	v_mfma_f32_16x16x32_bf16 v[20:23], v[150:153], v[212:215], v[20:23]
	v_mfma_f32_16x16x32_bf16 v[8:11], v[164:167], v[212:215], v[8:11]
	v_mfma_f32_16x16x32_bf16 v[60:63], v[160:163], v[192:195], v[60:63]
	v_mfma_f32_16x16x32_bf16 v[56:59], v[168:171], v[192:195], v[56:59]
	v_mfma_f32_16x16x32_bf16 v[52:55], v[160:163], v[200:203], v[52:55]
	v_mfma_f32_16x16x32_bf16 v[48:51], v[168:171], v[200:203], v[48:51]
	v_mfma_f32_16x16x32_bf16 v[44:47], v[160:163], v[208:211], v[44:47]
	v_mfma_f32_16x16x32_bf16 v[32:35], v[168:171], v[208:211], v[32:35]
	v_mfma_f32_16x16x32_bf16 v[20:23], v[160:163], v[216:219], v[20:23]
	v_mfma_f32_16x16x32_bf16 v[8:11], v[168:171], v[216:219], v[8:11]
	v_mfma_f32_16x16x32_bf16 v[40:43], v[172:175], v[188:191], v[40:43]
	v_mfma_f32_16x16x32_bf16 v[36:39], v[180:183], v[188:191], v[36:39]
	v_mfma_f32_16x16x32_bf16 v[28:31], v[172:175], v[196:199], v[28:31]
	v_mfma_f32_16x16x32_bf16 v[24:27], v[180:183], v[196:199], v[24:27]
	v_mfma_f32_16x16x32_bf16 v[16:19], v[172:175], v[204:207], v[16:19]
	v_mfma_f32_16x16x32_bf16 v[12:15], v[180:183], v[204:207], v[12:15]
	v_mfma_f32_16x16x32_bf16 v[4:7], v[172:175], v[212:215], v[4:7]
	v_mfma_f32_16x16x32_bf16 v[0:3], v[180:183], v[212:215], v[0:3]
	v_mfma_f32_16x16x32_bf16 v[40:43], v[176:179], v[192:195], v[40:43]
	v_mfma_f32_16x16x32_bf16 v[36:39], v[184:187], v[192:195], v[36:39]
	v_mfma_f32_16x16x32_bf16 v[28:31], v[176:179], v[200:203], v[28:31]
	v_mfma_f32_16x16x32_bf16 v[24:27], v[184:187], v[200:203], v[24:27]
	v_mfma_f32_16x16x32_bf16 v[16:19], v[176:179], v[208:211], v[16:19]
	v_mfma_f32_16x16x32_bf16 v[12:15], v[184:187], v[208:211], v[12:15]
	v_mfma_f32_16x16x32_bf16 v[4:7], v[176:179], v[216:219], v[4:7]
	v_mfma_f32_16x16x32_bf16 v[0:3], v[184:187], v[216:219], v[0:3]
	s_barrier
	s_add_i32 s56, s56, 2
	s_add_u32 s20, s20, 0x100
	s_addc_u32 s21, s21, 0
	s_add_u32 s54, s54, 0x100
	s_addc_u32 s55, s55, 0
	s_cmp_gt_u32 s56, 13
	s_cbranch_scc0 .LBB0_564
	s_and_b64 vcc, exec, s[10:11]
	s_cbranch_vccz .LBB0_567
	s_barrier
